# pk4 + redundant setprio 0/1 toggles between back-to-back MFMA clusters removed (20 sites, GEMM K-loops)
# speedup vs baseline: 1.0082x; 1.0082x over previous
.LBB0_397:
	s_add_u32 s24, s10, 0xfffc0080
	s_addc_u32 s25, s11, -1
	s_add_i32 s31, 0, 0x10000
	s_cmp_eq_u32 s30, 12
	s_cselect_b32 s27, s9, s25
	s_cselect_b32 s26, s13, s24
	v_add_u32_e32 v0, s31, v143
	s_cselect_b32 s25, s17, s29
	s_cselect_b32 s24, s19, s28
	s_add_i32 s52, 0, 0x14000
	ds_read_b128 v[152:155], v0
	ds_read_b128 v[166:169], v0 offset:1024
	ds_read_b128 v[170:173], v0 offset:2048
	ds_read_b128 v[174:177], v0 offset:3072
	v_add_u32_e32 v0, s52, v143
	ds_read_b128 v[198:201], v0
	ds_read_b128 v[202:205], v0 offset:1024
	ds_read_b128 v[206:209], v0 offset:2048
	ds_read_b128 v[210:213], v0 offset:3072
	v_lshl_add_u64 v[156:157], s[10:11], 0, v[148:149]
	s_add_i32 m0, s42, 0xc000
	ds_read_b128 v[214:217], v161
	ds_read_b128 v[218:221], v161 offset:1024
	ds_read_b128 v[222:225], v161 offset:2048
	ds_read_b128 v[226:229], v161 offset:3072
	ds_read_b128 v[230:233], v161 offset:4096
	ds_read_b128 v[234:237], v161 offset:5120
	ds_read_b128 v[238:241], v161 offset:6144
	ds_read_b128 v[242:245], v161 offset:7168
	global_load_lds_dwordx4 v[156:157], off
	v_lshl_add_u64 v[156:157], s[10:11], 0, v[150:151]
	s_add_i32 m0, s42, 0xe000
	s_nop 0
	global_load_lds_dwordx4 v[156:157], off
	s_waitcnt vmcnt(8)
	s_waitcnt lgkmcnt(0)
	s_barrier
	s_setprio 1
	s_waitcnt lgkmcnt(0)
	v_mfma_f32_16x16x32_bf16 v[126:129], v[152:155], v[214:217], v[126:129]
	v_mfma_f32_16x16x32_bf16 v[122:125], v[170:173], v[214:217], v[122:125]
	v_mfma_f32_16x16x32_bf16 v[110:113], v[152:155], v[222:225], v[110:113]
	v_mfma_f32_16x16x32_bf16 v[106:109], v[170:173], v[222:225], v[106:109]
	v_mfma_f32_16x16x32_bf16 v[94:97], v[152:155], v[230:233], v[94:97]
	v_mfma_f32_16x16x32_bf16 v[90:93], v[170:173], v[230:233], v[90:93]
	v_mfma_f32_16x16x32_bf16 v[78:81], v[152:155], v[238:241], v[78:81]
	v_mfma_f32_16x16x32_bf16 v[74:77], v[170:173], v[238:241], v[74:77]
	v_mfma_f32_16x16x32_bf16 v[126:129], v[166:169], v[218:221], v[126:129]
	v_mfma_f32_16x16x32_bf16 v[122:125], v[174:177], v[218:221], v[122:125]
	v_mfma_f32_16x16x32_bf16 v[110:113], v[166:169], v[226:229], v[110:113]
	v_mfma_f32_16x16x32_bf16 v[106:109], v[174:177], v[226:229], v[106:109]
	v_mfma_f32_16x16x32_bf16 v[94:97], v[166:169], v[234:237], v[94:97]
	v_mfma_f32_16x16x32_bf16 v[90:93], v[174:177], v[234:237], v[90:93]
	v_mfma_f32_16x16x32_bf16 v[78:81], v[166:169], v[242:245], v[78:81]
	v_mfma_f32_16x16x32_bf16 v[74:77], v[174:177], v[242:245], v[74:77]
	v_mfma_f32_16x16x32_bf16 v[118:121], v[198:201], v[214:217], v[118:121]
	v_mfma_f32_16x16x32_bf16 v[114:117], v[206:209], v[214:217], v[114:117]
	v_mfma_f32_16x16x32_bf16 v[102:105], v[198:201], v[222:225], v[102:105]
	v_mfma_f32_16x16x32_bf16 v[98:101], v[206:209], v[222:225], v[98:101]
	v_mfma_f32_16x16x32_bf16 v[86:89], v[198:201], v[230:233], v[86:89]
	v_mfma_f32_16x16x32_bf16 v[82:85], v[206:209], v[230:233], v[82:85]
	v_mfma_f32_16x16x32_bf16 v[70:73], v[198:201], v[238:241], v[70:73]
	v_mfma_f32_16x16x32_bf16 v[66:69], v[206:209], v[238:241], v[66:69]
	v_mfma_f32_16x16x32_bf16 v[118:121], v[202:205], v[218:221], v[118:121]
	v_mfma_f32_16x16x32_bf16 v[114:117], v[210:213], v[218:221], v[114:117]
	v_mfma_f32_16x16x32_bf16 v[102:105], v[202:205], v[226:229], v[102:105]
	v_mfma_f32_16x16x32_bf16 v[98:101], v[210:213], v[226:229], v[98:101]
	v_mfma_f32_16x16x32_bf16 v[86:89], v[202:205], v[234:237], v[86:89]
	v_mfma_f32_16x16x32_bf16 v[82:85], v[210:213], v[234:237], v[82:85]
	v_mfma_f32_16x16x32_bf16 v[70:73], v[202:205], v[242:245], v[70:73]
	v_mfma_f32_16x16x32_bf16 v[66:69], v[210:213], v[242:245], v[66:69]
	s_setprio 0
	s_barrier
	s_add_i32 s31, s31, s41
	v_lshl_add_u64 v[156:157], s[24:25], 0, v[132:133]
	s_mov_b32 m0, s31
	ds_read_b128 v[214:217], v161 offset:16384
	ds_read_b128 v[218:221], v161 offset:17408
	ds_read_b128 v[222:225], v161 offset:18432
	ds_read_b128 v[226:229], v161 offset:19456
	ds_read_b128 v[230:233], v161 offset:20480
	ds_read_b128 v[234:237], v161 offset:21504
	ds_read_b128 v[238:241], v161 offset:22528
	ds_read_b128 v[242:245], v161 offset:23552
	global_load_lds_dwordx4 v[156:157], off
	s_add_i32 m0, s31, 0x2000
	s_add_u32 s34, s24, 0x40000
	v_lshl_add_u64 v[178:179], s[24:25], 0, v[136:137]
	s_addc_u32 s35, s25, 0
	s_add_i32 s31, s52, s41
	global_load_lds_dwordx4 v[178:179], off
	v_lshl_add_u64 v[246:247], s[34:35], 0, v[132:133]
	s_mov_b32 m0, s31
	v_lshl_add_u64 v[248:249], s[26:27], 0, v[134:135]
	global_load_lds_dwordx4 v[246:247], off
	v_lshl_add_u64 v[246:247], s[34:35], 0, v[136:137]
	s_add_i32 m0, s31, 0x2000
	s_nop 0
	global_load_lds_dwordx4 v[246:247], off
	v_lshl_add_u64 v[246:247], s[26:27], 0, v[130:131]
	s_mov_b32 m0, s42
	s_nop 0
	global_load_lds_dwordx4 v[246:247], off
	s_mov_b32 m0, s43
	s_nop 0
	global_load_lds_dwordx4 v[248:249], off
	s_waitcnt vmcnt(8)
	s_waitcnt lgkmcnt(0)
	s_barrier
	s_setprio 1
	s_waitcnt lgkmcnt(0)
	v_mfma_f32_16x16x32_bf16 v[62:65], v[152:155], v[214:217], v[62:65]
	v_mfma_f32_16x16x32_bf16 v[58:61], v[170:173], v[214:217], v[58:61]
	v_mfma_f32_16x16x32_bf16 v[46:49], v[152:155], v[222:225], v[46:49]
	v_mfma_f32_16x16x32_bf16 v[42:45], v[170:173], v[222:225], v[42:45]
	v_mfma_f32_16x16x32_bf16 v[30:33], v[152:155], v[230:233], v[30:33]
	v_mfma_f32_16x16x32_bf16 v[26:29], v[170:173], v[230:233], v[26:29]
	v_mfma_f32_16x16x32_bf16 v[14:17], v[152:155], v[238:241], v[14:17]
	v_mfma_f32_16x16x32_bf16 v[10:13], v[170:173], v[238:241], v[10:13]
	v_mfma_f32_16x16x32_bf16 v[62:65], v[166:169], v[218:221], v[62:65]
	v_mfma_f32_16x16x32_bf16 v[58:61], v[174:177], v[218:221], v[58:61]
	v_mfma_f32_16x16x32_bf16 v[46:49], v[166:169], v[226:229], v[46:49]
	v_mfma_f32_16x16x32_bf16 v[42:45], v[174:177], v[226:229], v[42:45]
	v_mfma_f32_16x16x32_bf16 v[30:33], v[166:169], v[234:237], v[30:33]
	v_mfma_f32_16x16x32_bf16 v[26:29], v[174:177], v[234:237], v[26:29]
	v_mfma_f32_16x16x32_bf16 v[14:17], v[166:169], v[242:245], v[14:17]
	v_mfma_f32_16x16x32_bf16 v[10:13], v[174:177], v[242:245], v[10:13]
	v_mfma_f32_16x16x32_bf16 v[54:57], v[198:201], v[214:217], v[54:57]
	v_mfma_f32_16x16x32_bf16 v[50:53], v[206:209], v[214:217], v[50:53]
	v_mfma_f32_16x16x32_bf16 v[38:41], v[198:201], v[222:225], v[38:41]
	v_mfma_f32_16x16x32_bf16 v[34:37], v[206:209], v[222:225], v[34:37]
	v_mfma_f32_16x16x32_bf16 v[22:25], v[198:201], v[230:233], v[22:25]
	v_mfma_f32_16x16x32_bf16 v[18:21], v[206:209], v[230:233], v[18:21]
	v_mfma_f32_16x16x32_bf16 v[6:9], v[198:201], v[238:241], v[6:9]
	v_mfma_f32_16x16x32_bf16 v[2:5], v[206:209], v[238:241], v[2:5]
	v_mfma_f32_16x16x32_bf16 v[54:57], v[202:205], v[218:221], v[54:57]
	v_mfma_f32_16x16x32_bf16 v[50:53], v[210:213], v[218:221], v[50:53]
	v_mfma_f32_16x16x32_bf16 v[38:41], v[202:205], v[226:229], v[38:41]
	v_mfma_f32_16x16x32_bf16 v[34:37], v[210:213], v[226:229], v[34:37]
	v_mfma_f32_16x16x32_bf16 v[22:25], v[202:205], v[234:237], v[22:25]
	v_mfma_f32_16x16x32_bf16 v[18:21], v[210:213], v[234:237], v[18:21]
	v_mfma_f32_16x16x32_bf16 v[6:9], v[202:205], v[242:245], v[6:9]
	v_mfma_f32_16x16x32_bf16 v[2:5], v[210:213], v[242:245], v[2:5]
	s_setprio 0
	s_barrier
	s_add_i32 s31, 0, 0x18000
	v_add_u32_e32 v0, s31, v143
	s_add_i32 s34, 0, 0x1c000
	ds_read_b128 v[152:155], v0
	ds_read_b128 v[166:169], v0 offset:1024
	ds_read_b128 v[170:173], v0 offset:2048
	ds_read_b128 v[174:177], v0 offset:3072
	v_add_u32_e32 v0, s34, v143
	ds_read_b128 v[198:201], v0
	ds_read_b128 v[202:205], v0 offset:1024
	ds_read_b128 v[206:209], v0 offset:2048
	ds_read_b128 v[210:213], v0 offset:3072
	s_add_u32 s26, s26, 0x40000
	s_addc_u32 s27, s27, 0
	s_mov_b32 m0, s44
	v_lshl_add_u64 v[250:251], s[26:27], 0, v[130:131]
	ds_read_b128 v[214:217], v161 offset:32768
	ds_read_b128 v[218:221], v161 offset:33792
	ds_read_b128 v[222:225], v161 offset:34816
	ds_read_b128 v[226:229], v161 offset:35840
	ds_read_b128 v[230:233], v161 offset:36864
	ds_read_b128 v[234:237], v161 offset:37888
	ds_read_b128 v[238:241], v161 offset:38912
	ds_read_b128 v[242:245], v161 offset:39936
	global_load_lds_dwordx4 v[250:251], off
	v_lshl_add_u64 v[250:251], s[26:27], 0, v[134:135]
	s_mov_b32 m0, s45
	s_nop 0
	global_load_lds_dwordx4 v[250:251], off
	s_waitcnt vmcnt(8)
	s_waitcnt lgkmcnt(0)
	s_barrier
	s_setprio 1
	s_waitcnt lgkmcnt(0)
	v_mfma_f32_16x16x32_bf16 v[126:129], v[152:155], v[214:217], v[126:129]
	v_mfma_f32_16x16x32_bf16 v[122:125], v[170:173], v[214:217], v[122:125]
	v_mfma_f32_16x16x32_bf16 v[110:113], v[152:155], v[222:225], v[110:113]
	v_mfma_f32_16x16x32_bf16 v[106:109], v[170:173], v[222:225], v[106:109]
	v_mfma_f32_16x16x32_bf16 v[94:97], v[152:155], v[230:233], v[94:97]
	v_mfma_f32_16x16x32_bf16 v[90:93], v[170:173], v[230:233], v[90:93]
	v_mfma_f32_16x16x32_bf16 v[78:81], v[152:155], v[238:241], v[78:81]
	v_mfma_f32_16x16x32_bf16 v[74:77], v[170:173], v[238:241], v[74:77]
	v_mfma_f32_16x16x32_bf16 v[126:129], v[166:169], v[218:221], v[126:129]
	v_mfma_f32_16x16x32_bf16 v[122:125], v[174:177], v[218:221], v[122:125]
	v_mfma_f32_16x16x32_bf16 v[110:113], v[166:169], v[226:229], v[110:113]
	v_mfma_f32_16x16x32_bf16 v[106:109], v[174:177], v[226:229], v[106:109]
	v_mfma_f32_16x16x32_bf16 v[94:97], v[166:169], v[234:237], v[94:97]
	v_mfma_f32_16x16x32_bf16 v[90:93], v[174:177], v[234:237], v[90:93]
	v_mfma_f32_16x16x32_bf16 v[78:81], v[166:169], v[242:245], v[78:81]
	v_mfma_f32_16x16x32_bf16 v[74:77], v[174:177], v[242:245], v[74:77]
	v_mfma_f32_16x16x32_bf16 v[118:121], v[198:201], v[214:217], v[118:121]
	v_mfma_f32_16x16x32_bf16 v[114:117], v[206:209], v[214:217], v[114:117]
	v_mfma_f32_16x16x32_bf16 v[102:105], v[198:201], v[222:225], v[102:105]
	v_mfma_f32_16x16x32_bf16 v[98:101], v[206:209], v[222:225], v[98:101]
	v_mfma_f32_16x16x32_bf16 v[86:89], v[198:201], v[230:233], v[86:89]
	v_mfma_f32_16x16x32_bf16 v[82:85], v[206:209], v[230:233], v[82:85]
	v_mfma_f32_16x16x32_bf16 v[70:73], v[198:201], v[238:241], v[70:73]
	v_mfma_f32_16x16x32_bf16 v[66:69], v[206:209], v[238:241], v[66:69]
	v_mfma_f32_16x16x32_bf16 v[118:121], v[202:205], v[218:221], v[118:121]
	v_mfma_f32_16x16x32_bf16 v[114:117], v[210:213], v[218:221], v[114:117]
	v_mfma_f32_16x16x32_bf16 v[102:105], v[202:205], v[226:229], v[102:105]
	v_mfma_f32_16x16x32_bf16 v[98:101], v[210:213], v[226:229], v[98:101]
	v_mfma_f32_16x16x32_bf16 v[86:89], v[202:205], v[234:237], v[86:89]
	v_mfma_f32_16x16x32_bf16 v[82:85], v[210:213], v[234:237], v[82:85]
	v_mfma_f32_16x16x32_bf16 v[70:73], v[202:205], v[242:245], v[70:73]
	v_mfma_f32_16x16x32_bf16 v[66:69], v[210:213], v[242:245], v[66:69]
	s_setprio 0
	s_barrier
	s_add_i32 s26, s31, s41
	v_lshl_add_u64 v[156:157], v[156:157], 0, s[88:89]
	s_mov_b32 m0, s26
	ds_read_b128 v[214:217], v161 offset:49152
	ds_read_b128 v[218:221], v161 offset:50176
	ds_read_b128 v[222:225], v161 offset:51200
	ds_read_b128 v[226:229], v161 offset:52224
	ds_read_b128 v[230:233], v161 offset:53248
	ds_read_b128 v[234:237], v161 offset:54272
	ds_read_b128 v[238:241], v161 offset:55296
	ds_read_b128 v[242:245], v161 offset:56320
	global_load_lds_dwordx4 v[156:157], off
	s_add_i32 m0, s26, 0x2000
	s_add_u32 s24, s24, 0x40080
	v_lshl_add_u64 v[156:157], v[178:179], 0, s[88:89]
	s_addc_u32 s25, s25, 0
	s_add_i32 s26, s34, s41
	global_load_lds_dwordx4 v[156:157], off
	v_lshl_add_u64 v[156:157], s[24:25], 0, v[132:133]
	s_mov_b32 m0, s26
	s_nop 0
	global_load_lds_dwordx4 v[156:157], off
	v_lshl_add_u64 v[156:157], s[24:25], 0, v[136:137]
	s_add_i32 m0, s26, 0x2000
	s_nop 0
	global_load_lds_dwordx4 v[156:157], off
	v_lshl_add_u64 v[156:157], v[246:247], 0, s[88:89]
	s_mov_b32 m0, s47
	s_nop 0
	global_load_lds_dwordx4 v[156:157], off
	v_lshl_add_u64 v[156:157], v[248:249], 0, s[88:89]
	s_mov_b32 m0, s48
	s_nop 0
	global_load_lds_dwordx4 v[156:157], off
	s_waitcnt vmcnt(8)
	s_waitcnt lgkmcnt(0)
	s_barrier
	s_setprio 1
	s_waitcnt lgkmcnt(0)
	v_mfma_f32_16x16x32_bf16 v[62:65], v[152:155], v[214:217], v[62:65]
	v_mfma_f32_16x16x32_bf16 v[58:61], v[170:173], v[214:217], v[58:61]
	v_mfma_f32_16x16x32_bf16 v[46:49], v[152:155], v[222:225], v[46:49]
	v_mfma_f32_16x16x32_bf16 v[42:45], v[170:173], v[222:225], v[42:45]
	v_mfma_f32_16x16x32_bf16 v[30:33], v[152:155], v[230:233], v[30:33]
	v_mfma_f32_16x16x32_bf16 v[26:29], v[170:173], v[230:233], v[26:29]
	v_mfma_f32_16x16x32_bf16 v[14:17], v[152:155], v[238:241], v[14:17]
	v_mfma_f32_16x16x32_bf16 v[10:13], v[170:173], v[238:241], v[10:13]
	v_mfma_f32_16x16x32_bf16 v[62:65], v[166:169], v[218:221], v[62:65]
	v_mfma_f32_16x16x32_bf16 v[58:61], v[174:177], v[218:221], v[58:61]
	v_mfma_f32_16x16x32_bf16 v[46:49], v[166:169], v[226:229], v[46:49]
	v_mfma_f32_16x16x32_bf16 v[42:45], v[174:177], v[226:229], v[42:45]
	v_mfma_f32_16x16x32_bf16 v[30:33], v[166:169], v[234:237], v[30:33]
	v_mfma_f32_16x16x32_bf16 v[26:29], v[174:177], v[234:237], v[26:29]
	v_mfma_f32_16x16x32_bf16 v[14:17], v[166:169], v[242:245], v[14:17]
	v_mfma_f32_16x16x32_bf16 v[10:13], v[174:177], v[242:245], v[10:13]
	v_mfma_f32_16x16x32_bf16 v[54:57], v[198:201], v[214:217], v[54:57]
	v_mfma_f32_16x16x32_bf16 v[50:53], v[206:209], v[214:217], v[50:53]
	v_mfma_f32_16x16x32_bf16 v[38:41], v[198:201], v[222:225], v[38:41]
	v_mfma_f32_16x16x32_bf16 v[34:37], v[206:209], v[222:225], v[34:37]
	v_mfma_f32_16x16x32_bf16 v[22:25], v[198:201], v[230:233], v[22:25]
	v_mfma_f32_16x16x32_bf16 v[18:21], v[206:209], v[230:233], v[18:21]
	v_mfma_f32_16x16x32_bf16 v[6:9], v[198:201], v[238:241], v[6:9]
	v_mfma_f32_16x16x32_bf16 v[2:5], v[206:209], v[238:241], v[2:5]
	v_mfma_f32_16x16x32_bf16 v[54:57], v[202:205], v[218:221], v[54:57]
	v_mfma_f32_16x16x32_bf16 v[50:53], v[210:213], v[218:221], v[50:53]
	v_mfma_f32_16x16x32_bf16 v[38:41], v[202:205], v[226:229], v[38:41]
	v_mfma_f32_16x16x32_bf16 v[34:37], v[210:213], v[226:229], v[34:37]
	v_mfma_f32_16x16x32_bf16 v[22:25], v[202:205], v[234:237], v[22:25]
	v_mfma_f32_16x16x32_bf16 v[18:21], v[210:213], v[234:237], v[18:21]
	v_mfma_f32_16x16x32_bf16 v[6:9], v[202:205], v[242:245], v[6:9]
	v_mfma_f32_16x16x32_bf16 v[2:5], v[210:213], v[242:245], v[2:5]
	s_setprio 0
	s_barrier
	s_add_i32 s30, s30, 2
	s_add_u32 s10, s10, 0x100
	s_addc_u32 s11, s11, 0
	s_add_u32 s28, s28, 0x100
	s_addc_u32 s29, s29, 0
	s_cmp_gt_u32 s30, 13
	s_cbranch_scc0 .LBB0_397
	s_and_b64 vcc, exec, s[14:15]
	s_cbranch_vccz .LBB0_400
	s_barrier

.LBB0_1084:
	s_add_i32 s59, s59, 2
	s_add_u32 s34, s30, s80
	s_addc_u32 s35, s31, 0
	s_add_u32 s61, s28, s80
	s_addc_u32 s62, s29, 0
	s_add_i32 s63, 0, 0x10000
	s_cmp_eq_u32 s80, s26
	s_cselect_b32 s37, s15, s35
	s_cselect_b32 s36, s33, s34
	v_add_u32_e32 v0, s63, v148
	s_cselect_b32 s35, s54, s62
	s_cselect_b32 s34, s55, s61
	s_add_i32 s61, 0, 0x14000
	ds_read_b128 v[166:169], v0
	ds_read_b128 v[170:173], v0 offset:1024
	ds_read_b128 v[174:177], v0 offset:2048
	ds_read_b128 v[198:201], v0 offset:3072
	v_add_u32_e32 v0, s61, v148
	ds_read_b128 v[202:205], v0
	ds_read_b128 v[206:209], v0 offset:1024
	ds_read_b128 v[210:213], v0 offset:2048
	ds_read_b128 v[214:217], v0 offset:3072
	v_lshl_add_u64 v[178:179], v[146:147], 0, s[80:81]
	s_add_i32 m0, s46, 0xc000
	ds_read_b128 v[218:221], v150
	ds_read_b128 v[222:225], v150 offset:1024
	ds_read_b128 v[226:229], v150 offset:2048
	ds_read_b128 v[230:233], v150 offset:3072
	ds_read_b128 v[234:237], v150 offset:4096
	ds_read_b128 v[238:241], v150 offset:5120
	ds_read_b128 v[242:245], v150 offset:6144
	ds_read_b128 v[246:249], v150 offset:7168
	global_load_lds_dwordx4 v[178:179], off
	v_lshl_add_u64 v[178:179], v[2:3], 0, s[80:81]
	s_add_i32 m0, s46, 0xe000
	s_nop 0
	global_load_lds_dwordx4 v[178:179], off
	s_waitcnt vmcnt(8)
	s_waitcnt lgkmcnt(0)
	s_barrier
	s_setprio 1
	s_waitcnt lgkmcnt(0)
	v_mfma_f32_16x16x32_bf16 v[128:131], v[166:169], v[218:221], v[128:131]
	v_mfma_f32_16x16x32_bf16 v[124:127], v[174:177], v[218:221], v[124:127]
	v_mfma_f32_16x16x32_bf16 v[112:115], v[166:169], v[226:229], v[112:115]
	v_mfma_f32_16x16x32_bf16 v[108:111], v[174:177], v[226:229], v[108:111]
	v_mfma_f32_16x16x32_bf16 v[96:99], v[166:169], v[234:237], v[96:99]
	v_mfma_f32_16x16x32_bf16 v[92:95], v[174:177], v[234:237], v[92:95]
	v_mfma_f32_16x16x32_bf16 v[80:83], v[166:169], v[242:245], v[80:83]
	v_mfma_f32_16x16x32_bf16 v[76:79], v[174:177], v[242:245], v[76:79]
	v_mfma_f32_16x16x32_bf16 v[128:131], v[170:173], v[222:225], v[128:131]
	v_mfma_f32_16x16x32_bf16 v[124:127], v[198:201], v[222:225], v[124:127]
	v_mfma_f32_16x16x32_bf16 v[112:115], v[170:173], v[230:233], v[112:115]
	v_mfma_f32_16x16x32_bf16 v[108:111], v[198:201], v[230:233], v[108:111]
	v_mfma_f32_16x16x32_bf16 v[96:99], v[170:173], v[238:241], v[96:99]
	v_mfma_f32_16x16x32_bf16 v[92:95], v[198:201], v[238:241], v[92:95]
	v_mfma_f32_16x16x32_bf16 v[80:83], v[170:173], v[246:249], v[80:83]
	v_mfma_f32_16x16x32_bf16 v[76:79], v[198:201], v[246:249], v[76:79]
	v_mfma_f32_16x16x32_bf16 v[120:123], v[202:205], v[218:221], v[120:123]
	v_mfma_f32_16x16x32_bf16 v[116:119], v[210:213], v[218:221], v[116:119]
	v_mfma_f32_16x16x32_bf16 v[104:107], v[202:205], v[226:229], v[104:107]
	v_mfma_f32_16x16x32_bf16 v[100:103], v[210:213], v[226:229], v[100:103]
	v_mfma_f32_16x16x32_bf16 v[88:91], v[202:205], v[234:237], v[88:91]
	v_mfma_f32_16x16x32_bf16 v[84:87], v[210:213], v[234:237], v[84:87]
	v_mfma_f32_16x16x32_bf16 v[72:75], v[202:205], v[242:245], v[72:75]
	v_mfma_f32_16x16x32_bf16 v[68:71], v[210:213], v[242:245], v[68:71]
	v_mfma_f32_16x16x32_bf16 v[120:123], v[206:209], v[222:225], v[120:123]
	v_mfma_f32_16x16x32_bf16 v[116:119], v[214:217], v[222:225], v[116:119]
	v_mfma_f32_16x16x32_bf16 v[104:107], v[206:209], v[230:233], v[104:107]
	v_mfma_f32_16x16x32_bf16 v[100:103], v[214:217], v[230:233], v[100:103]
	v_mfma_f32_16x16x32_bf16 v[88:91], v[206:209], v[238:241], v[88:91]
	v_mfma_f32_16x16x32_bf16 v[84:87], v[214:217], v[238:241], v[84:87]
	v_mfma_f32_16x16x32_bf16 v[72:75], v[206:209], v[246:249], v[72:75]
	v_mfma_f32_16x16x32_bf16 v[68:71], v[214:217], v[246:249], v[68:71]
	s_setprio 0
	s_barrier
	s_add_i32 s62, s63, s45
	v_lshl_add_u64 v[178:179], s[34:35], 0, v[132:133]
	s_mov_b32 m0, s62
	ds_read_b128 v[218:221], v150 offset:16384
	ds_read_b128 v[222:225], v150 offset:17408
	ds_read_b128 v[226:229], v150 offset:18432
	ds_read_b128 v[230:233], v150 offset:19456
	ds_read_b128 v[234:237], v150 offset:20480
	ds_read_b128 v[238:241], v150 offset:21504
	ds_read_b128 v[242:245], v150 offset:22528
	ds_read_b128 v[246:249], v150 offset:23552
	global_load_lds_dwordx4 v[178:179], off
	s_add_i32 m0, s62, 0x2000
	s_add_u32 s62, s34, 0x40000
	v_lshl_add_u64 v[250:251], s[34:35], 0, v[134:135]
	s_addc_u32 s63, s35, 0
	s_add_i32 s61, s61, s45
	global_load_lds_dwordx4 v[250:251], off
	v_lshl_add_u64 v[252:253], s[62:63], 0, v[132:133]
	s_mov_b32 m0, s61
	v_lshl_add_u64 v[162:163], s[36:37], 0, v[134:135]
	global_load_lds_dwordx4 v[252:253], off
	v_lshl_add_u64 v[252:253], s[62:63], 0, v[134:135]
	s_add_i32 m0, s61, 0x2000
	s_nop 0
	global_load_lds_dwordx4 v[252:253], off
	v_lshl_add_u64 v[252:253], s[36:37], 0, v[132:133]
	s_mov_b32 m0, s46
	s_nop 0
	global_load_lds_dwordx4 v[252:253], off
	s_mov_b32 m0, s47
	s_nop 0
	global_load_lds_dwordx4 v[162:163], off
	s_waitcnt vmcnt(8)
	s_waitcnt lgkmcnt(0)
	s_barrier
	s_setprio 1
	s_waitcnt lgkmcnt(0)
	v_mfma_f32_16x16x32_bf16 v[64:67], v[166:169], v[218:221], v[64:67]
	v_mfma_f32_16x16x32_bf16 v[60:63], v[174:177], v[218:221], v[60:63]
	v_mfma_f32_16x16x32_bf16 v[48:51], v[166:169], v[226:229], v[48:51]
	v_mfma_f32_16x16x32_bf16 v[44:47], v[174:177], v[226:229], v[44:47]
	v_mfma_f32_16x16x32_bf16 v[32:35], v[166:169], v[234:237], v[32:35]
	v_mfma_f32_16x16x32_bf16 v[28:31], v[174:177], v[234:237], v[28:31]
	v_mfma_f32_16x16x32_bf16 v[16:19], v[166:169], v[242:245], v[16:19]
	v_mfma_f32_16x16x32_bf16 v[12:15], v[174:177], v[242:245], v[12:15]
	v_mfma_f32_16x16x32_bf16 v[64:67], v[170:173], v[222:225], v[64:67]
	v_mfma_f32_16x16x32_bf16 v[60:63], v[198:201], v[222:225], v[60:63]
	v_mfma_f32_16x16x32_bf16 v[48:51], v[170:173], v[230:233], v[48:51]
	v_mfma_f32_16x16x32_bf16 v[44:47], v[198:201], v[230:233], v[44:47]
	v_mfma_f32_16x16x32_bf16 v[32:35], v[170:173], v[238:241], v[32:35]
	v_mfma_f32_16x16x32_bf16 v[28:31], v[198:201], v[238:241], v[28:31]
	v_mfma_f32_16x16x32_bf16 v[16:19], v[170:173], v[246:249], v[16:19]
	v_mfma_f32_16x16x32_bf16 v[12:15], v[198:201], v[246:249], v[12:15]
	v_mfma_f32_16x16x32_bf16 v[56:59], v[202:205], v[218:221], v[56:59]
	v_mfma_f32_16x16x32_bf16 v[52:55], v[210:213], v[218:221], v[52:55]
	v_mfma_f32_16x16x32_bf16 v[40:43], v[202:205], v[226:229], v[40:43]
	v_mfma_f32_16x16x32_bf16 v[36:39], v[210:213], v[226:229], v[36:39]
	v_mfma_f32_16x16x32_bf16 v[24:27], v[202:205], v[234:237], v[24:27]
	v_mfma_f32_16x16x32_bf16 v[20:23], v[210:213], v[234:237], v[20:23]
	v_mfma_f32_16x16x32_bf16 v[8:11], v[202:205], v[242:245], v[8:11]
	v_mfma_f32_16x16x32_bf16 v[4:7], v[210:213], v[242:245], v[4:7]
	v_mfma_f32_16x16x32_bf16 v[56:59], v[206:209], v[222:225], v[56:59]
	v_mfma_f32_16x16x32_bf16 v[52:55], v[214:217], v[222:225], v[52:55]
	v_mfma_f32_16x16x32_bf16 v[40:43], v[206:209], v[230:233], v[40:43]
	v_mfma_f32_16x16x32_bf16 v[36:39], v[214:217], v[230:233], v[36:39]
	v_mfma_f32_16x16x32_bf16 v[24:27], v[206:209], v[238:241], v[24:27]
	v_mfma_f32_16x16x32_bf16 v[20:23], v[214:217], v[238:241], v[20:23]
	v_mfma_f32_16x16x32_bf16 v[8:11], v[206:209], v[246:249], v[8:11]
	v_mfma_f32_16x16x32_bf16 v[4:7], v[214:217], v[246:249], v[4:7]
	s_setprio 0
	s_barrier
	s_add_i32 s61, 0, 0x18000
	v_add_u32_e32 v0, s61, v148
	s_add_i32 s62, 0, 0x1c000
	ds_read_b128 v[166:169], v0
	ds_read_b128 v[170:173], v0 offset:1024
	ds_read_b128 v[174:177], v0 offset:2048
	ds_read_b128 v[198:201], v0 offset:3072
	v_add_u32_e32 v0, s62, v148
	ds_read_b128 v[202:205], v0
	ds_read_b128 v[206:209], v0 offset:1024
	ds_read_b128 v[210:213], v0 offset:2048
	ds_read_b128 v[214:217], v0 offset:3072
	s_add_u32 s36, s36, 0x40000
	s_addc_u32 s37, s37, 0
	s_mov_b32 m0, s48
	v_lshl_add_u64 v[164:165], s[36:37], 0, v[132:133]
	ds_read_b128 v[218:221], v150 offset:32768
	ds_read_b128 v[222:225], v150 offset:33792
	ds_read_b128 v[226:229], v150 offset:34816
	ds_read_b128 v[230:233], v150 offset:35840
	ds_read_b128 v[234:237], v150 offset:36864
	ds_read_b128 v[238:241], v150 offset:37888
	ds_read_b128 v[242:245], v150 offset:38912
	ds_read_b128 v[246:249], v150 offset:39936
	global_load_lds_dwordx4 v[164:165], off
	v_lshl_add_u64 v[164:165], s[36:37], 0, v[134:135]
	s_mov_b32 m0, s49
	s_nop 0
	global_load_lds_dwordx4 v[164:165], off
	s_waitcnt vmcnt(8)
	s_waitcnt lgkmcnt(0)
	s_barrier
	s_setprio 1
	s_waitcnt lgkmcnt(0)
	v_mfma_f32_16x16x32_bf16 v[128:131], v[166:169], v[218:221], v[128:131]
	v_mfma_f32_16x16x32_bf16 v[124:127], v[174:177], v[218:221], v[124:127]
	v_mfma_f32_16x16x32_bf16 v[112:115], v[166:169], v[226:229], v[112:115]
	v_mfma_f32_16x16x32_bf16 v[108:111], v[174:177], v[226:229], v[108:111]
	v_mfma_f32_16x16x32_bf16 v[96:99], v[166:169], v[234:237], v[96:99]
	v_mfma_f32_16x16x32_bf16 v[92:95], v[174:177], v[234:237], v[92:95]
	v_mfma_f32_16x16x32_bf16 v[80:83], v[166:169], v[242:245], v[80:83]
	v_mfma_f32_16x16x32_bf16 v[76:79], v[174:177], v[242:245], v[76:79]
	v_mfma_f32_16x16x32_bf16 v[128:131], v[170:173], v[222:225], v[128:131]
	v_mfma_f32_16x16x32_bf16 v[124:127], v[198:201], v[222:225], v[124:127]
	v_mfma_f32_16x16x32_bf16 v[112:115], v[170:173], v[230:233], v[112:115]
	v_mfma_f32_16x16x32_bf16 v[108:111], v[198:201], v[230:233], v[108:111]
	v_mfma_f32_16x16x32_bf16 v[96:99], v[170:173], v[238:241], v[96:99]
	v_mfma_f32_16x16x32_bf16 v[92:95], v[198:201], v[238:241], v[92:95]
	v_mfma_f32_16x16x32_bf16 v[80:83], v[170:173], v[246:249], v[80:83]
	v_mfma_f32_16x16x32_bf16 v[76:79], v[198:201], v[246:249], v[76:79]
	v_mfma_f32_16x16x32_bf16 v[120:123], v[202:205], v[218:221], v[120:123]
	v_mfma_f32_16x16x32_bf16 v[116:119], v[210:213], v[218:221], v[116:119]
	v_mfma_f32_16x16x32_bf16 v[104:107], v[202:205], v[226:229], v[104:107]
	v_mfma_f32_16x16x32_bf16 v[100:103], v[210:213], v[226:229], v[100:103]
	v_mfma_f32_16x16x32_bf16 v[88:91], v[202:205], v[234:237], v[88:91]
	v_mfma_f32_16x16x32_bf16 v[84:87], v[210:213], v[234:237], v[84:87]
	v_mfma_f32_16x16x32_bf16 v[72:75], v[202:205], v[242:245], v[72:75]
	v_mfma_f32_16x16x32_bf16 v[68:71], v[210:213], v[242:245], v[68:71]
	v_mfma_f32_16x16x32_bf16 v[120:123], v[206:209], v[222:225], v[120:123]
	v_mfma_f32_16x16x32_bf16 v[116:119], v[214:217], v[222:225], v[116:119]
	v_mfma_f32_16x16x32_bf16 v[104:107], v[206:209], v[230:233], v[104:107]
	v_mfma_f32_16x16x32_bf16 v[100:103], v[214:217], v[230:233], v[100:103]
	v_mfma_f32_16x16x32_bf16 v[88:91], v[206:209], v[238:241], v[88:91]
	v_mfma_f32_16x16x32_bf16 v[84:87], v[214:217], v[238:241], v[84:87]
	v_mfma_f32_16x16x32_bf16 v[72:75], v[206:209], v[246:249], v[72:75]
	v_mfma_f32_16x16x32_bf16 v[68:71], v[214:217], v[246:249], v[68:71]
	s_setprio 0
	s_barrier
	s_add_i32 s36, s61, s45
	v_lshl_add_u64 v[164:165], v[178:179], 0, s[88:89]
	s_mov_b32 m0, s36
	ds_read_b128 v[218:221], v150 offset:49152
	ds_read_b128 v[222:225], v150 offset:50176
	ds_read_b128 v[226:229], v150 offset:51200
	ds_read_b128 v[230:233], v150 offset:52224
	ds_read_b128 v[234:237], v150 offset:53248
	ds_read_b128 v[238:241], v150 offset:54272
	ds_read_b128 v[242:245], v150 offset:55296
	ds_read_b128 v[246:249], v150 offset:56320
	global_load_lds_dwordx4 v[164:165], off
	s_add_i32 m0, s36, 0x2000
	s_add_u32 s34, s34, 0x40080
	v_lshl_add_u64 v[164:165], v[250:251], 0, s[88:89]
	s_addc_u32 s35, s35, 0
	s_add_i32 s36, s62, s45
	global_load_lds_dwordx4 v[164:165], off
	v_lshl_add_u64 v[164:165], s[34:35], 0, v[132:133]
	s_mov_b32 m0, s36
	v_lshl_add_u64 v[162:163], v[162:163], 0, s[88:89]
	global_load_lds_dwordx4 v[164:165], off
	v_lshl_add_u64 v[164:165], s[34:35], 0, v[134:135]
	s_add_i32 m0, s36, 0x2000
	s_nop 0
	global_load_lds_dwordx4 v[164:165], off
	v_lshl_add_u64 v[164:165], v[252:253], 0, s[88:89]
	s_mov_b32 m0, s50
	s_nop 0
	global_load_lds_dwordx4 v[164:165], off
	s_mov_b32 m0, s51
	s_nop 0
	global_load_lds_dwordx4 v[162:163], off
	s_waitcnt vmcnt(8)
	s_waitcnt lgkmcnt(0)
	s_barrier
	s_setprio 1
	s_waitcnt lgkmcnt(0)
	v_mfma_f32_16x16x32_bf16 v[64:67], v[166:169], v[218:221], v[64:67]
	v_mfma_f32_16x16x32_bf16 v[60:63], v[174:177], v[218:221], v[60:63]
	v_mfma_f32_16x16x32_bf16 v[48:51], v[166:169], v[226:229], v[48:51]
	v_mfma_f32_16x16x32_bf16 v[44:47], v[174:177], v[226:229], v[44:47]
	v_mfma_f32_16x16x32_bf16 v[32:35], v[166:169], v[234:237], v[32:35]
	v_mfma_f32_16x16x32_bf16 v[28:31], v[174:177], v[234:237], v[28:31]
	v_mfma_f32_16x16x32_bf16 v[16:19], v[166:169], v[242:245], v[16:19]
	v_mfma_f32_16x16x32_bf16 v[12:15], v[174:177], v[242:245], v[12:15]
	v_mfma_f32_16x16x32_bf16 v[64:67], v[170:173], v[222:225], v[64:67]
	v_mfma_f32_16x16x32_bf16 v[60:63], v[198:201], v[222:225], v[60:63]
	v_mfma_f32_16x16x32_bf16 v[48:51], v[170:173], v[230:233], v[48:51]
	v_mfma_f32_16x16x32_bf16 v[44:47], v[198:201], v[230:233], v[44:47]
	v_mfma_f32_16x16x32_bf16 v[32:35], v[170:173], v[238:241], v[32:35]
	v_mfma_f32_16x16x32_bf16 v[28:31], v[198:201], v[238:241], v[28:31]
	v_mfma_f32_16x16x32_bf16 v[16:19], v[170:173], v[246:249], v[16:19]
	v_mfma_f32_16x16x32_bf16 v[12:15], v[198:201], v[246:249], v[12:15]
	v_mfma_f32_16x16x32_bf16 v[56:59], v[202:205], v[218:221], v[56:59]
	v_mfma_f32_16x16x32_bf16 v[52:55], v[210:213], v[218:221], v[52:55]
	v_mfma_f32_16x16x32_bf16 v[40:43], v[202:205], v[226:229], v[40:43]
	v_mfma_f32_16x16x32_bf16 v[36:39], v[210:213], v[226:229], v[36:39]
	v_mfma_f32_16x16x32_bf16 v[24:27], v[202:205], v[234:237], v[24:27]
	v_mfma_f32_16x16x32_bf16 v[20:23], v[210:213], v[234:237], v[20:23]
	v_mfma_f32_16x16x32_bf16 v[8:11], v[202:205], v[242:245], v[8:11]
	v_mfma_f32_16x16x32_bf16 v[4:7], v[210:213], v[242:245], v[4:7]
	v_mfma_f32_16x16x32_bf16 v[56:59], v[206:209], v[222:225], v[56:59]
	v_mfma_f32_16x16x32_bf16 v[52:55], v[214:217], v[222:225], v[52:55]
	v_mfma_f32_16x16x32_bf16 v[40:43], v[206:209], v[230:233], v[40:43]
	v_mfma_f32_16x16x32_bf16 v[36:39], v[214:217], v[230:233], v[36:39]
	v_mfma_f32_16x16x32_bf16 v[24:27], v[206:209], v[238:241], v[24:27]
	v_mfma_f32_16x16x32_bf16 v[20:23], v[214:217], v[238:241], v[20:23]
	v_mfma_f32_16x16x32_bf16 v[8:11], v[206:209], v[246:249], v[8:11]
	v_mfma_f32_16x16x32_bf16 v[4:7], v[214:217], v[246:249], v[4:7]
	s_setprio 0
	s_barrier
	s_add_u32 s30, s30, 0x100
	s_addc_u32 s31, s31, 0
	s_add_u32 s28, s28, 0x100
	s_addc_u32 s29, s29, 0
	s_add_u32 s26, s26, 0xffffff00
	s_addc_u32 s27, s27, -1
	v_lshl_add_u64 v[146:147], v[146:147], 0, s[70:71]
	s_cmp_ge_u32 s59, s60
	v_lshl_add_u64 v[2:3], v[2:3], 0, s[70:71]
	s_cbranch_scc0 .LBB0_1084
	s_branch .LBB0_1079

.LBB0_1154:
	s_add_u32 s30, s28, 0x100
	s_addc_u32 s31, s29, 0
	s_add_i32 s57, 0, 0x10000
	s_cmp_eq_u32 s56, 12
	s_cselect_b32 s37, s19, s31
	s_cselect_b32 s36, s25, s30
	s_cselect_b32 s35, s17, s55
	s_cselect_b32 s34, s27, s54
	s_add_i32 s58, 0, 0x14000
	v_add_u32_e32 v152, s57, v149
	v_add_u32_e32 v161, s58, v149
	ds_read_b128 v[136:139], v152
	ds_read_b128 v[140:143], v152 offset:1024
	ds_read_b128 v[144:147], v152 offset:2048
	ds_read_b128 v[152:155], v152 offset:3072
	ds_read_b128 v[156:159], v161
	ds_read_b128 v[166:169], v161 offset:1024
	ds_read_b128 v[170:173], v161 offset:2048
	ds_read_b128 v[174:177], v161 offset:3072
	v_lshl_add_u64 v[162:163], s[28:29], 0, v[132:133]
	s_add_i32 m0, s44, 0xc000
	ds_read_b128 v[198:201], v151
	ds_read_b128 v[202:205], v151 offset:1024
	ds_read_b128 v[206:209], v151 offset:2048
	ds_read_b128 v[210:213], v151 offset:3072
	ds_read_b128 v[214:217], v151 offset:4096
	ds_read_b128 v[218:221], v151 offset:5120
	ds_read_b128 v[222:225], v151 offset:6144
	ds_read_b128 v[226:229], v151 offset:7168
	global_load_lds_dwordx4 v[162:163], off
	v_lshl_add_u64 v[162:163], s[28:29], 0, v[134:135]
	s_add_i32 m0, s44, 0xe000
	s_nop 0
	global_load_lds_dwordx4 v[162:163], off
	s_waitcnt vmcnt(8)
	s_waitcnt lgkmcnt(0)
	s_barrier
	s_setprio 1
	s_waitcnt lgkmcnt(0)
	v_mfma_f32_16x16x32_bf16 v[126:129], v[136:139], v[198:201], v[126:129]
	v_mfma_f32_16x16x32_bf16 v[122:125], v[144:147], v[198:201], v[122:125]
	v_mfma_f32_16x16x32_bf16 v[110:113], v[136:139], v[206:209], v[110:113]
	v_mfma_f32_16x16x32_bf16 v[106:109], v[144:147], v[206:209], v[106:109]
	v_mfma_f32_16x16x32_bf16 v[94:97], v[136:139], v[214:217], v[94:97]
	v_mfma_f32_16x16x32_bf16 v[90:93], v[144:147], v[214:217], v[90:93]
	v_mfma_f32_16x16x32_bf16 v[78:81], v[136:139], v[222:225], v[78:81]
	v_mfma_f32_16x16x32_bf16 v[74:77], v[144:147], v[222:225], v[74:77]
	v_mfma_f32_16x16x32_bf16 v[126:129], v[140:143], v[202:205], v[126:129]
	v_mfma_f32_16x16x32_bf16 v[122:125], v[152:155], v[202:205], v[122:125]
	v_mfma_f32_16x16x32_bf16 v[110:113], v[140:143], v[210:213], v[110:113]
	v_mfma_f32_16x16x32_bf16 v[106:109], v[152:155], v[210:213], v[106:109]
	v_mfma_f32_16x16x32_bf16 v[94:97], v[140:143], v[218:221], v[94:97]
	v_mfma_f32_16x16x32_bf16 v[90:93], v[152:155], v[218:221], v[90:93]
	v_mfma_f32_16x16x32_bf16 v[78:81], v[140:143], v[226:229], v[78:81]
	v_mfma_f32_16x16x32_bf16 v[74:77], v[152:155], v[226:229], v[74:77]
	v_mfma_f32_16x16x32_bf16 v[118:121], v[156:159], v[198:201], v[118:121]
	v_mfma_f32_16x16x32_bf16 v[114:117], v[170:173], v[198:201], v[114:117]
	v_mfma_f32_16x16x32_bf16 v[102:105], v[156:159], v[206:209], v[102:105]
	v_mfma_f32_16x16x32_bf16 v[98:101], v[170:173], v[206:209], v[98:101]
	v_mfma_f32_16x16x32_bf16 v[86:89], v[156:159], v[214:217], v[86:89]
	v_mfma_f32_16x16x32_bf16 v[82:85], v[170:173], v[214:217], v[82:85]
	v_mfma_f32_16x16x32_bf16 v[70:73], v[156:159], v[222:225], v[70:73]
	v_mfma_f32_16x16x32_bf16 v[66:69], v[170:173], v[222:225], v[66:69]
	v_mfma_f32_16x16x32_bf16 v[118:121], v[166:169], v[202:205], v[118:121]
	v_mfma_f32_16x16x32_bf16 v[114:117], v[174:177], v[202:205], v[114:117]
	v_mfma_f32_16x16x32_bf16 v[102:105], v[166:169], v[210:213], v[102:105]
	v_mfma_f32_16x16x32_bf16 v[98:101], v[174:177], v[210:213], v[98:101]
	v_mfma_f32_16x16x32_bf16 v[86:89], v[166:169], v[218:221], v[86:89]
	v_mfma_f32_16x16x32_bf16 v[82:85], v[174:177], v[218:221], v[82:85]
	v_mfma_f32_16x16x32_bf16 v[70:73], v[166:169], v[226:229], v[70:73]
	v_mfma_f32_16x16x32_bf16 v[66:69], v[174:177], v[226:229], v[66:69]
	s_setprio 0
	s_barrier
	s_add_i32 s28, s57, s43
	v_lshl_add_u64 v[162:163], s[34:35], 0, v[0:1]
	s_mov_b32 m0, s28
	ds_read_b128 v[198:201], v151 offset:16384
	ds_read_b128 v[202:205], v151 offset:17408
	ds_read_b128 v[206:209], v151 offset:18432
	ds_read_b128 v[210:213], v151 offset:19456
	ds_read_b128 v[214:217], v151 offset:20480
	ds_read_b128 v[218:221], v151 offset:21504
	ds_read_b128 v[222:225], v151 offset:22528
	ds_read_b128 v[226:229], v151 offset:23552
	global_load_lds_dwordx4 v[162:163], off
	s_add_i32 m0, s28, 0x2000
	s_add_u32 s28, s34, 0x40000
	v_lshl_add_u64 v[164:165], s[34:35], 0, v[130:131]
	s_addc_u32 s29, s35, 0
	s_add_i32 s57, s58, s43
	global_load_lds_dwordx4 v[164:165], off
	v_lshl_add_u64 v[178:179], s[28:29], 0, v[0:1]
	s_mov_b32 m0, s57
	v_lshl_add_u64 v[230:231], s[36:37], 0, v[130:131]
	global_load_lds_dwordx4 v[178:179], off
	v_lshl_add_u64 v[178:179], s[28:29], 0, v[130:131]
	s_add_i32 m0, s57, 0x2000
	s_nop 0
	global_load_lds_dwordx4 v[178:179], off
	v_lshl_add_u64 v[178:179], s[36:37], 0, v[0:1]
	s_mov_b32 m0, s44
	s_nop 0
	global_load_lds_dwordx4 v[178:179], off
	s_mov_b32 m0, s45
	s_nop 0
	global_load_lds_dwordx4 v[230:231], off
	s_waitcnt vmcnt(8)
	s_waitcnt lgkmcnt(0)
	s_barrier
	s_setprio 1
	s_waitcnt lgkmcnt(0)
	v_mfma_f32_16x16x32_bf16 v[62:65], v[136:139], v[198:201], v[62:65]
	v_mfma_f32_16x16x32_bf16 v[58:61], v[144:147], v[198:201], v[58:61]
	v_mfma_f32_16x16x32_bf16 v[46:49], v[136:139], v[206:209], v[46:49]
	v_mfma_f32_16x16x32_bf16 v[42:45], v[144:147], v[206:209], v[42:45]
	v_mfma_f32_16x16x32_bf16 v[30:33], v[136:139], v[214:217], v[30:33]
	v_mfma_f32_16x16x32_bf16 v[26:29], v[144:147], v[214:217], v[26:29]
	v_mfma_f32_16x16x32_bf16 v[14:17], v[136:139], v[222:225], v[14:17]
	v_mfma_f32_16x16x32_bf16 v[10:13], v[144:147], v[222:225], v[10:13]
	v_mfma_f32_16x16x32_bf16 v[62:65], v[140:143], v[202:205], v[62:65]
	v_mfma_f32_16x16x32_bf16 v[58:61], v[152:155], v[202:205], v[58:61]
	v_mfma_f32_16x16x32_bf16 v[46:49], v[140:143], v[210:213], v[46:49]
	v_mfma_f32_16x16x32_bf16 v[42:45], v[152:155], v[210:213], v[42:45]
	v_mfma_f32_16x16x32_bf16 v[30:33], v[140:143], v[218:221], v[30:33]
	v_mfma_f32_16x16x32_bf16 v[26:29], v[152:155], v[218:221], v[26:29]
	v_mfma_f32_16x16x32_bf16 v[14:17], v[140:143], v[226:229], v[14:17]
	v_mfma_f32_16x16x32_bf16 v[10:13], v[152:155], v[226:229], v[10:13]
	v_mfma_f32_16x16x32_bf16 v[54:57], v[156:159], v[198:201], v[54:57]
	v_mfma_f32_16x16x32_bf16 v[50:53], v[170:173], v[198:201], v[50:53]
	v_mfma_f32_16x16x32_bf16 v[38:41], v[156:159], v[206:209], v[38:41]
	v_mfma_f32_16x16x32_bf16 v[34:37], v[170:173], v[206:209], v[34:37]
	v_mfma_f32_16x16x32_bf16 v[22:25], v[156:159], v[214:217], v[22:25]
	v_mfma_f32_16x16x32_bf16 v[18:21], v[170:173], v[214:217], v[18:21]
	v_mfma_f32_16x16x32_bf16 v[6:9], v[156:159], v[222:225], v[6:9]
	v_mfma_f32_16x16x32_bf16 v[2:5], v[170:173], v[222:225], v[2:5]
	v_mfma_f32_16x16x32_bf16 v[54:57], v[166:169], v[202:205], v[54:57]
	v_mfma_f32_16x16x32_bf16 v[50:53], v[174:177], v[202:205], v[50:53]
	v_mfma_f32_16x16x32_bf16 v[38:41], v[166:169], v[210:213], v[38:41]
	v_mfma_f32_16x16x32_bf16 v[34:37], v[174:177], v[210:213], v[34:37]
	v_mfma_f32_16x16x32_bf16 v[22:25], v[166:169], v[218:221], v[22:25]
	v_mfma_f32_16x16x32_bf16 v[18:21], v[174:177], v[218:221], v[18:21]
	v_mfma_f32_16x16x32_bf16 v[6:9], v[166:169], v[226:229], v[6:9]
	v_mfma_f32_16x16x32_bf16 v[2:5], v[174:177], v[226:229], v[2:5]
	s_setprio 0
	s_barrier
	s_add_i32 s57, 0, 0x18000
	s_add_i32 s58, 0, 0x1c000
	v_add_u32_e32 v152, s57, v149
	v_add_u32_e32 v161, s58, v149
	ds_read_b128 v[136:139], v152
	ds_read_b128 v[140:143], v152 offset:1024
	ds_read_b128 v[144:147], v152 offset:2048
	ds_read_b128 v[152:155], v152 offset:3072
	ds_read_b128 v[156:159], v161
	ds_read_b128 v[166:169], v161 offset:1024
	ds_read_b128 v[170:173], v161 offset:2048
	ds_read_b128 v[174:177], v161 offset:3072
	s_add_u32 s28, s36, 0x40000
	s_addc_u32 s29, s37, 0
	s_mov_b32 m0, s46
	v_lshl_add_u64 v[232:233], s[28:29], 0, v[0:1]
	ds_read_b128 v[198:201], v151 offset:32768
	ds_read_b128 v[202:205], v151 offset:33792
	ds_read_b128 v[206:209], v151 offset:34816
	ds_read_b128 v[210:213], v151 offset:35840
	ds_read_b128 v[214:217], v151 offset:36864
	ds_read_b128 v[218:221], v151 offset:37888
	ds_read_b128 v[222:225], v151 offset:38912
	ds_read_b128 v[226:229], v151 offset:39936
	global_load_lds_dwordx4 v[232:233], off
	v_lshl_add_u64 v[232:233], s[28:29], 0, v[130:131]
	s_mov_b32 m0, s47
	s_nop 0
	global_load_lds_dwordx4 v[232:233], off
	s_waitcnt vmcnt(8)
	s_waitcnt lgkmcnt(0)
	s_barrier
	s_setprio 1
	s_waitcnt lgkmcnt(0)
	v_mfma_f32_16x16x32_bf16 v[126:129], v[136:139], v[198:201], v[126:129]
	v_mfma_f32_16x16x32_bf16 v[122:125], v[144:147], v[198:201], v[122:125]
	v_mfma_f32_16x16x32_bf16 v[110:113], v[136:139], v[206:209], v[110:113]
	v_mfma_f32_16x16x32_bf16 v[106:109], v[144:147], v[206:209], v[106:109]
	v_mfma_f32_16x16x32_bf16 v[94:97], v[136:139], v[214:217], v[94:97]
	v_mfma_f32_16x16x32_bf16 v[90:93], v[144:147], v[214:217], v[90:93]
	v_mfma_f32_16x16x32_bf16 v[78:81], v[136:139], v[222:225], v[78:81]
	v_mfma_f32_16x16x32_bf16 v[74:77], v[144:147], v[222:225], v[74:77]
	v_mfma_f32_16x16x32_bf16 v[126:129], v[140:143], v[202:205], v[126:129]
	v_mfma_f32_16x16x32_bf16 v[122:125], v[152:155], v[202:205], v[122:125]
	v_mfma_f32_16x16x32_bf16 v[110:113], v[140:143], v[210:213], v[110:113]
	v_mfma_f32_16x16x32_bf16 v[106:109], v[152:155], v[210:213], v[106:109]
	v_mfma_f32_16x16x32_bf16 v[94:97], v[140:143], v[218:221], v[94:97]
	v_mfma_f32_16x16x32_bf16 v[90:93], v[152:155], v[218:221], v[90:93]
	v_mfma_f32_16x16x32_bf16 v[78:81], v[140:143], v[226:229], v[78:81]
	v_mfma_f32_16x16x32_bf16 v[74:77], v[152:155], v[226:229], v[74:77]
	v_mfma_f32_16x16x32_bf16 v[118:121], v[156:159], v[198:201], v[118:121]
	v_mfma_f32_16x16x32_bf16 v[114:117], v[170:173], v[198:201], v[114:117]
	v_mfma_f32_16x16x32_bf16 v[102:105], v[156:159], v[206:209], v[102:105]
	v_mfma_f32_16x16x32_bf16 v[98:101], v[170:173], v[206:209], v[98:101]
	v_mfma_f32_16x16x32_bf16 v[86:89], v[156:159], v[214:217], v[86:89]
	v_mfma_f32_16x16x32_bf16 v[82:85], v[170:173], v[214:217], v[82:85]
	v_mfma_f32_16x16x32_bf16 v[70:73], v[156:159], v[222:225], v[70:73]
	v_mfma_f32_16x16x32_bf16 v[66:69], v[170:173], v[222:225], v[66:69]
	v_mfma_f32_16x16x32_bf16 v[118:121], v[166:169], v[202:205], v[118:121]
	v_mfma_f32_16x16x32_bf16 v[114:117], v[174:177], v[202:205], v[114:117]
	v_mfma_f32_16x16x32_bf16 v[102:105], v[166:169], v[210:213], v[102:105]
	v_mfma_f32_16x16x32_bf16 v[98:101], v[174:177], v[210:213], v[98:101]
	v_mfma_f32_16x16x32_bf16 v[86:89], v[166:169], v[218:221], v[86:89]
	v_mfma_f32_16x16x32_bf16 v[82:85], v[174:177], v[218:221], v[82:85]
	v_mfma_f32_16x16x32_bf16 v[70:73], v[166:169], v[226:229], v[70:73]
	v_mfma_f32_16x16x32_bf16 v[66:69], v[174:177], v[226:229], v[66:69]
	s_setprio 0
	s_barrier
	s_add_i32 s28, s57, s43
	v_lshl_add_u64 v[162:163], v[162:163], 0, s[88:89]
	s_mov_b32 m0, s28
	ds_read_b128 v[198:201], v151 offset:49152
	ds_read_b128 v[202:205], v151 offset:50176
	ds_read_b128 v[206:209], v151 offset:51200
	ds_read_b128 v[210:213], v151 offset:52224
	ds_read_b128 v[214:217], v151 offset:53248
	ds_read_b128 v[218:221], v151 offset:54272
	ds_read_b128 v[222:225], v151 offset:55296
	ds_read_b128 v[226:229], v151 offset:56320
	global_load_lds_dwordx4 v[162:163], off
	s_add_i32 m0, s28, 0x2000
	s_add_u32 s28, s34, 0x40080
	v_lshl_add_u64 v[162:163], v[164:165], 0, s[88:89]
	s_addc_u32 s29, s35, 0
	s_add_i32 s34, s58, s43
	global_load_lds_dwordx4 v[162:163], off
	v_lshl_add_u64 v[162:163], s[28:29], 0, v[0:1]
	s_mov_b32 m0, s34
	s_nop 0
	global_load_lds_dwordx4 v[162:163], off
	v_lshl_add_u64 v[162:163], s[28:29], 0, v[130:131]
	s_add_i32 m0, s34, 0x2000
	s_nop 0
	global_load_lds_dwordx4 v[162:163], off
	v_lshl_add_u64 v[162:163], v[178:179], 0, s[88:89]
	s_mov_b32 m0, s49
	s_nop 0
	global_load_lds_dwordx4 v[162:163], off
	v_lshl_add_u64 v[162:163], v[230:231], 0, s[88:89]
	s_mov_b32 m0, s50
	s_nop 0
	global_load_lds_dwordx4 v[162:163], off
	s_waitcnt vmcnt(8)
	s_waitcnt lgkmcnt(0)
	s_barrier
	s_setprio 1
	s_waitcnt lgkmcnt(0)
	v_mfma_f32_16x16x32_bf16 v[62:65], v[136:139], v[198:201], v[62:65]
	v_mfma_f32_16x16x32_bf16 v[58:61], v[144:147], v[198:201], v[58:61]
	v_mfma_f32_16x16x32_bf16 v[46:49], v[136:139], v[206:209], v[46:49]
	v_mfma_f32_16x16x32_bf16 v[42:45], v[144:147], v[206:209], v[42:45]
	v_mfma_f32_16x16x32_bf16 v[30:33], v[136:139], v[214:217], v[30:33]
	v_mfma_f32_16x16x32_bf16 v[26:29], v[144:147], v[214:217], v[26:29]
	v_mfma_f32_16x16x32_bf16 v[14:17], v[136:139], v[222:225], v[14:17]
	v_mfma_f32_16x16x32_bf16 v[10:13], v[144:147], v[222:225], v[10:13]
	v_mfma_f32_16x16x32_bf16 v[62:65], v[140:143], v[202:205], v[62:65]
	v_mfma_f32_16x16x32_bf16 v[58:61], v[152:155], v[202:205], v[58:61]
	v_mfma_f32_16x16x32_bf16 v[46:49], v[140:143], v[210:213], v[46:49]
	v_mfma_f32_16x16x32_bf16 v[42:45], v[152:155], v[210:213], v[42:45]
	v_mfma_f32_16x16x32_bf16 v[30:33], v[140:143], v[218:221], v[30:33]
	v_mfma_f32_16x16x32_bf16 v[26:29], v[152:155], v[218:221], v[26:29]
	v_mfma_f32_16x16x32_bf16 v[14:17], v[140:143], v[226:229], v[14:17]
	v_mfma_f32_16x16x32_bf16 v[10:13], v[152:155], v[226:229], v[10:13]
	v_mfma_f32_16x16x32_bf16 v[54:57], v[156:159], v[198:201], v[54:57]
	v_mfma_f32_16x16x32_bf16 v[50:53], v[170:173], v[198:201], v[50:53]
	v_mfma_f32_16x16x32_bf16 v[38:41], v[156:159], v[206:209], v[38:41]
	v_mfma_f32_16x16x32_bf16 v[34:37], v[170:173], v[206:209], v[34:37]
	v_mfma_f32_16x16x32_bf16 v[22:25], v[156:159], v[214:217], v[22:25]
	v_mfma_f32_16x16x32_bf16 v[18:21], v[170:173], v[214:217], v[18:21]
	v_mfma_f32_16x16x32_bf16 v[6:9], v[156:159], v[222:225], v[6:9]
	v_mfma_f32_16x16x32_bf16 v[2:5], v[170:173], v[222:225], v[2:5]
	v_mfma_f32_16x16x32_bf16 v[54:57], v[166:169], v[202:205], v[54:57]
	v_mfma_f32_16x16x32_bf16 v[50:53], v[174:177], v[202:205], v[50:53]
	v_mfma_f32_16x16x32_bf16 v[38:41], v[166:169], v[210:213], v[38:41]
	v_mfma_f32_16x16x32_bf16 v[34:37], v[174:177], v[210:213], v[34:37]
	v_mfma_f32_16x16x32_bf16 v[22:25], v[166:169], v[218:221], v[22:25]
	v_mfma_f32_16x16x32_bf16 v[18:21], v[174:177], v[218:221], v[18:21]
	v_mfma_f32_16x16x32_bf16 v[6:9], v[166:169], v[226:229], v[6:9]
	v_mfma_f32_16x16x32_bf16 v[2:5], v[174:177], v[226:229], v[2:5]
	s_setprio 0
	s_barrier
	s_add_i32 s56, s56, 2
	s_add_u32 s54, s54, 0x100
	s_addc_u32 s55, s55, 0
	s_cmp_gt_u32 s56, 13
	s_mov_b64 s[28:29], s[30:31]
	s_cbranch_scc0 .LBB0_1154
	s_and_b64 vcc, exec, s[14:15]
	s_cbranch_vccz .LBB0_1157
	s_barrier

.LBB0_1240:
	s_add_u32 s24, s22, 0xfffc0080
	s_addc_u32 s25, s23, -1
	s_add_i32 s48, 0, 0x10000
	s_cmp_eq_u32 s47, 12
	s_cselect_b32 s27, s1, s25
	s_cselect_b32 s26, s9, s24
	v_add_u32_e32 v144, s48, v147
	s_cselect_b32 s25, s15, s46
	s_cselect_b32 s24, s17, s45
	s_add_i32 s50, 0, 0x14000
	ds_read_b128 v[140:143], v144
	ds_read_b128 v[150:153], v144 offset:1024
	ds_read_b128 v[154:157], v144 offset:2048
	ds_read_b128 v[166:169], v144 offset:3072
	v_add_u32_e32 v144, s50, v147
	ds_read_b128 v[170:173], v144
	ds_read_b128 v[174:177], v144 offset:1024
	ds_read_b128 v[198:201], v144 offset:2048
	ds_read_b128 v[202:205], v144 offset:3072
	v_lshl_add_u64 v[144:145], s[22:23], 0, v[136:137]
	s_add_i32 m0, s36, 0xc000
	ds_read_b128 v[206:209], v149
	ds_read_b128 v[210:213], v149 offset:1024
	ds_read_b128 v[214:217], v149 offset:2048
	ds_read_b128 v[218:221], v149 offset:3072
	ds_read_b128 v[222:225], v149 offset:4096
	ds_read_b128 v[226:229], v149 offset:5120
	ds_read_b128 v[230:233], v149 offset:6144
	ds_read_b128 v[234:237], v149 offset:7168
	global_load_lds_dwordx4 v[144:145], off
	v_lshl_add_u64 v[144:145], s[22:23], 0, v[138:139]
	s_add_i32 m0, s36, 0xe000
	s_nop 0
	global_load_lds_dwordx4 v[144:145], off
	s_waitcnt vmcnt(8)
	s_waitcnt lgkmcnt(0)
	s_barrier
	s_setprio 1
	s_waitcnt lgkmcnt(0)
	v_mfma_f32_16x16x32_bf16 v[126:129], v[140:143], v[206:209], v[126:129]
	v_mfma_f32_16x16x32_bf16 v[122:125], v[154:157], v[206:209], v[122:125]
	v_mfma_f32_16x16x32_bf16 v[110:113], v[140:143], v[214:217], v[110:113]
	v_mfma_f32_16x16x32_bf16 v[106:109], v[154:157], v[214:217], v[106:109]
	v_mfma_f32_16x16x32_bf16 v[94:97], v[140:143], v[222:225], v[94:97]
	v_mfma_f32_16x16x32_bf16 v[90:93], v[154:157], v[222:225], v[90:93]
	v_mfma_f32_16x16x32_bf16 v[78:81], v[140:143], v[230:233], v[78:81]
	v_mfma_f32_16x16x32_bf16 v[74:77], v[154:157], v[230:233], v[74:77]
	v_mfma_f32_16x16x32_bf16 v[126:129], v[150:153], v[210:213], v[126:129]
	v_mfma_f32_16x16x32_bf16 v[122:125], v[166:169], v[210:213], v[122:125]
	v_mfma_f32_16x16x32_bf16 v[110:113], v[150:153], v[218:221], v[110:113]
	v_mfma_f32_16x16x32_bf16 v[106:109], v[166:169], v[218:221], v[106:109]
	v_mfma_f32_16x16x32_bf16 v[94:97], v[150:153], v[226:229], v[94:97]
	v_mfma_f32_16x16x32_bf16 v[90:93], v[166:169], v[226:229], v[90:93]
	v_mfma_f32_16x16x32_bf16 v[78:81], v[150:153], v[234:237], v[78:81]
	v_mfma_f32_16x16x32_bf16 v[74:77], v[166:169], v[234:237], v[74:77]
	v_mfma_f32_16x16x32_bf16 v[118:121], v[170:173], v[206:209], v[118:121]
	v_mfma_f32_16x16x32_bf16 v[114:117], v[198:201], v[206:209], v[114:117]
	v_mfma_f32_16x16x32_bf16 v[102:105], v[170:173], v[214:217], v[102:105]
	v_mfma_f32_16x16x32_bf16 v[98:101], v[198:201], v[214:217], v[98:101]
	v_mfma_f32_16x16x32_bf16 v[86:89], v[170:173], v[222:225], v[86:89]
	v_mfma_f32_16x16x32_bf16 v[82:85], v[198:201], v[222:225], v[82:85]
	v_mfma_f32_16x16x32_bf16 v[70:73], v[170:173], v[230:233], v[70:73]
	v_mfma_f32_16x16x32_bf16 v[66:69], v[198:201], v[230:233], v[66:69]
	v_mfma_f32_16x16x32_bf16 v[118:121], v[174:177], v[210:213], v[118:121]
	v_mfma_f32_16x16x32_bf16 v[114:117], v[202:205], v[210:213], v[114:117]
	v_mfma_f32_16x16x32_bf16 v[102:105], v[174:177], v[218:221], v[102:105]
	v_mfma_f32_16x16x32_bf16 v[98:101], v[202:205], v[218:221], v[98:101]
	v_mfma_f32_16x16x32_bf16 v[86:89], v[174:177], v[226:229], v[86:89]
	v_mfma_f32_16x16x32_bf16 v[82:85], v[202:205], v[226:229], v[82:85]
	v_mfma_f32_16x16x32_bf16 v[70:73], v[174:177], v[234:237], v[70:73]
	v_mfma_f32_16x16x32_bf16 v[66:69], v[202:205], v[234:237], v[66:69]
	s_setprio 0
	s_barrier
	s_add_i32 s48, s48, s35
	v_lshl_add_u64 v[144:145], s[24:25], 0, v[0:1]
	s_mov_b32 m0, s48
	ds_read_b128 v[206:209], v149 offset:16384
	ds_read_b128 v[210:213], v149 offset:17408
	ds_read_b128 v[214:217], v149 offset:18432
	ds_read_b128 v[218:221], v149 offset:19456
	ds_read_b128 v[222:225], v149 offset:20480
	ds_read_b128 v[226:229], v149 offset:21504
	ds_read_b128 v[230:233], v149 offset:22528
	ds_read_b128 v[234:237], v149 offset:23552
	global_load_lds_dwordx4 v[144:145], off
	s_add_i32 m0, s48, 0x2000
	s_add_u32 s48, s24, 0x40000
	v_lshl_add_u64 v[158:159], s[24:25], 0, v[134:135]
	s_addc_u32 s49, s25, 0
	s_add_i32 s50, s50, s35
	global_load_lds_dwordx4 v[158:159], off
	v_lshl_add_u64 v[162:163], s[48:49], 0, v[0:1]
	s_mov_b32 m0, s50
	v_lshl_add_u64 v[164:165], s[26:27], 0, v[132:133]
	global_load_lds_dwordx4 v[162:163], off
	v_lshl_add_u64 v[162:163], s[48:49], 0, v[134:135]
	s_add_i32 m0, s50, 0x2000
	s_nop 0
	global_load_lds_dwordx4 v[162:163], off
	v_lshl_add_u64 v[162:163], s[26:27], 0, v[130:131]
	s_mov_b32 m0, s36
	s_nop 0
	global_load_lds_dwordx4 v[162:163], off
	s_mov_b32 m0, s37
	s_nop 0
	global_load_lds_dwordx4 v[164:165], off
	s_waitcnt vmcnt(8)
	s_waitcnt lgkmcnt(0)
	s_barrier
	s_setprio 1
	s_waitcnt lgkmcnt(0)
	v_mfma_f32_16x16x32_bf16 v[62:65], v[140:143], v[206:209], v[62:65]
	v_mfma_f32_16x16x32_bf16 v[58:61], v[154:157], v[206:209], v[58:61]
	v_mfma_f32_16x16x32_bf16 v[46:49], v[140:143], v[214:217], v[46:49]
	v_mfma_f32_16x16x32_bf16 v[42:45], v[154:157], v[214:217], v[42:45]
	v_mfma_f32_16x16x32_bf16 v[30:33], v[140:143], v[222:225], v[30:33]
	v_mfma_f32_16x16x32_bf16 v[26:29], v[154:157], v[222:225], v[26:29]
	v_mfma_f32_16x16x32_bf16 v[14:17], v[140:143], v[230:233], v[14:17]
	v_mfma_f32_16x16x32_bf16 v[10:13], v[154:157], v[230:233], v[10:13]
	v_mfma_f32_16x16x32_bf16 v[62:65], v[150:153], v[210:213], v[62:65]
	v_mfma_f32_16x16x32_bf16 v[58:61], v[166:169], v[210:213], v[58:61]
	v_mfma_f32_16x16x32_bf16 v[46:49], v[150:153], v[218:221], v[46:49]
	v_mfma_f32_16x16x32_bf16 v[42:45], v[166:169], v[218:221], v[42:45]
	v_mfma_f32_16x16x32_bf16 v[30:33], v[150:153], v[226:229], v[30:33]
	v_mfma_f32_16x16x32_bf16 v[26:29], v[166:169], v[226:229], v[26:29]
	v_mfma_f32_16x16x32_bf16 v[14:17], v[150:153], v[234:237], v[14:17]
	v_mfma_f32_16x16x32_bf16 v[10:13], v[166:169], v[234:237], v[10:13]
	v_mfma_f32_16x16x32_bf16 v[54:57], v[170:173], v[206:209], v[54:57]
	v_mfma_f32_16x16x32_bf16 v[50:53], v[198:201], v[206:209], v[50:53]
	v_mfma_f32_16x16x32_bf16 v[38:41], v[170:173], v[214:217], v[38:41]
	v_mfma_f32_16x16x32_bf16 v[34:37], v[198:201], v[214:217], v[34:37]
	v_mfma_f32_16x16x32_bf16 v[22:25], v[170:173], v[222:225], v[22:25]
	v_mfma_f32_16x16x32_bf16 v[18:21], v[198:201], v[222:225], v[18:21]
	v_mfma_f32_16x16x32_bf16 v[6:9], v[170:173], v[230:233], v[6:9]
	v_mfma_f32_16x16x32_bf16 v[2:5], v[198:201], v[230:233], v[2:5]
	v_mfma_f32_16x16x32_bf16 v[54:57], v[174:177], v[210:213], v[54:57]
	v_mfma_f32_16x16x32_bf16 v[50:53], v[202:205], v[210:213], v[50:53]
	v_mfma_f32_16x16x32_bf16 v[38:41], v[174:177], v[218:221], v[38:41]
	v_mfma_f32_16x16x32_bf16 v[34:37], v[202:205], v[218:221], v[34:37]
	v_mfma_f32_16x16x32_bf16 v[22:25], v[174:177], v[226:229], v[22:25]
	v_mfma_f32_16x16x32_bf16 v[18:21], v[202:205], v[226:229], v[18:21]
	v_mfma_f32_16x16x32_bf16 v[6:9], v[174:177], v[234:237], v[6:9]
	v_mfma_f32_16x16x32_bf16 v[2:5], v[202:205], v[234:237], v[2:5]
	s_setprio 0
	s_barrier
	s_add_i32 s48, 0, 0x18000
	v_add_u32_e32 v161, s48, v147
	s_add_i32 s49, 0, 0x1c000
	ds_read_b128 v[140:143], v161
	ds_read_b128 v[150:153], v161 offset:1024
	ds_read_b128 v[154:157], v161 offset:2048
	ds_read_b128 v[166:169], v161 offset:3072
	v_add_u32_e32 v161, s49, v147
	ds_read_b128 v[170:173], v161
	ds_read_b128 v[174:177], v161 offset:1024
	ds_read_b128 v[198:201], v161 offset:2048
	ds_read_b128 v[202:205], v161 offset:3072
	s_add_u32 s26, s26, 0x40000
	s_addc_u32 s27, s27, 0
	s_mov_b32 m0, s38
	v_lshl_add_u64 v[178:179], s[26:27], 0, v[130:131]
	ds_read_b128 v[206:209], v149 offset:32768
	ds_read_b128 v[210:213], v149 offset:33792
	ds_read_b128 v[214:217], v149 offset:34816
	ds_read_b128 v[218:221], v149 offset:35840
	ds_read_b128 v[222:225], v149 offset:36864
	ds_read_b128 v[226:229], v149 offset:37888
	ds_read_b128 v[230:233], v149 offset:38912
	ds_read_b128 v[234:237], v149 offset:39936
	global_load_lds_dwordx4 v[178:179], off
	v_lshl_add_u64 v[178:179], s[26:27], 0, v[132:133]
	s_mov_b32 m0, s39
	s_nop 0
	global_load_lds_dwordx4 v[178:179], off
	s_waitcnt vmcnt(8)
	s_waitcnt lgkmcnt(0)
	s_barrier
	s_setprio 1
	s_waitcnt lgkmcnt(0)
	v_mfma_f32_16x16x32_bf16 v[126:129], v[140:143], v[206:209], v[126:129]
	v_mfma_f32_16x16x32_bf16 v[122:125], v[154:157], v[206:209], v[122:125]
	v_mfma_f32_16x16x32_bf16 v[110:113], v[140:143], v[214:217], v[110:113]
	v_mfma_f32_16x16x32_bf16 v[106:109], v[154:157], v[214:217], v[106:109]
	v_mfma_f32_16x16x32_bf16 v[94:97], v[140:143], v[222:225], v[94:97]
	v_mfma_f32_16x16x32_bf16 v[90:93], v[154:157], v[222:225], v[90:93]
	v_mfma_f32_16x16x32_bf16 v[78:81], v[140:143], v[230:233], v[78:81]
	v_mfma_f32_16x16x32_bf16 v[74:77], v[154:157], v[230:233], v[74:77]
	v_mfma_f32_16x16x32_bf16 v[126:129], v[150:153], v[210:213], v[126:129]
	v_mfma_f32_16x16x32_bf16 v[122:125], v[166:169], v[210:213], v[122:125]
	v_mfma_f32_16x16x32_bf16 v[110:113], v[150:153], v[218:221], v[110:113]
	v_mfma_f32_16x16x32_bf16 v[106:109], v[166:169], v[218:221], v[106:109]
	v_mfma_f32_16x16x32_bf16 v[94:97], v[150:153], v[226:229], v[94:97]
	v_mfma_f32_16x16x32_bf16 v[90:93], v[166:169], v[226:229], v[90:93]
	v_mfma_f32_16x16x32_bf16 v[78:81], v[150:153], v[234:237], v[78:81]
	v_mfma_f32_16x16x32_bf16 v[74:77], v[166:169], v[234:237], v[74:77]
	v_mfma_f32_16x16x32_bf16 v[118:121], v[170:173], v[206:209], v[118:121]
	v_mfma_f32_16x16x32_bf16 v[114:117], v[198:201], v[206:209], v[114:117]
	v_mfma_f32_16x16x32_bf16 v[102:105], v[170:173], v[214:217], v[102:105]
	v_mfma_f32_16x16x32_bf16 v[98:101], v[198:201], v[214:217], v[98:101]
	v_mfma_f32_16x16x32_bf16 v[86:89], v[170:173], v[222:225], v[86:89]
	v_mfma_f32_16x16x32_bf16 v[82:85], v[198:201], v[222:225], v[82:85]
	v_mfma_f32_16x16x32_bf16 v[70:73], v[170:173], v[230:233], v[70:73]
	v_mfma_f32_16x16x32_bf16 v[66:69], v[198:201], v[230:233], v[66:69]
	v_mfma_f32_16x16x32_bf16 v[118:121], v[174:177], v[210:213], v[118:121]
	v_mfma_f32_16x16x32_bf16 v[114:117], v[202:205], v[210:213], v[114:117]
	v_mfma_f32_16x16x32_bf16 v[102:105], v[174:177], v[218:221], v[102:105]
	v_mfma_f32_16x16x32_bf16 v[98:101], v[202:205], v[218:221], v[98:101]
	v_mfma_f32_16x16x32_bf16 v[86:89], v[174:177], v[226:229], v[86:89]
	v_mfma_f32_16x16x32_bf16 v[82:85], v[202:205], v[226:229], v[82:85]
	v_mfma_f32_16x16x32_bf16 v[70:73], v[174:177], v[234:237], v[70:73]
	v_mfma_f32_16x16x32_bf16 v[66:69], v[202:205], v[234:237], v[66:69]
	s_setprio 0
	s_barrier
	s_add_i32 s26, s48, s35
	v_lshl_add_u64 v[144:145], v[144:145], 0, s[88:89]
	s_mov_b32 m0, s26
	ds_read_b128 v[206:209], v149 offset:49152
	ds_read_b128 v[210:213], v149 offset:50176
	ds_read_b128 v[214:217], v149 offset:51200
	ds_read_b128 v[218:221], v149 offset:52224
	ds_read_b128 v[222:225], v149 offset:53248
	ds_read_b128 v[226:229], v149 offset:54272
	ds_read_b128 v[230:233], v149 offset:55296
	ds_read_b128 v[234:237], v149 offset:56320
	global_load_lds_dwordx4 v[144:145], off
	s_add_i32 m0, s26, 0x2000
	s_add_u32 s24, s24, 0x40080
	v_lshl_add_u64 v[144:145], v[158:159], 0, s[88:89]
	s_addc_u32 s25, s25, 0
	s_add_i32 s26, s49, s35
	global_load_lds_dwordx4 v[144:145], off
	v_lshl_add_u64 v[144:145], s[24:25], 0, v[0:1]
	s_mov_b32 m0, s26
	s_nop 0
	global_load_lds_dwordx4 v[144:145], off
	v_lshl_add_u64 v[144:145], s[24:25], 0, v[134:135]
	s_add_i32 m0, s26, 0x2000
	s_nop 0
	global_load_lds_dwordx4 v[144:145], off
	v_lshl_add_u64 v[144:145], v[162:163], 0, s[88:89]
	s_mov_b32 m0, s40
	s_nop 0
	global_load_lds_dwordx4 v[144:145], off
	v_lshl_add_u64 v[144:145], v[164:165], 0, s[88:89]
	s_mov_b32 m0, s41
	s_nop 0
	global_load_lds_dwordx4 v[144:145], off
	s_waitcnt vmcnt(8)
	s_waitcnt lgkmcnt(0)
	s_barrier
	s_setprio 1
	s_waitcnt lgkmcnt(0)
	v_mfma_f32_16x16x32_bf16 v[62:65], v[140:143], v[206:209], v[62:65]
	v_mfma_f32_16x16x32_bf16 v[58:61], v[154:157], v[206:209], v[58:61]
	v_mfma_f32_16x16x32_bf16 v[46:49], v[140:143], v[214:217], v[46:49]
	v_mfma_f32_16x16x32_bf16 v[42:45], v[154:157], v[214:217], v[42:45]
	v_mfma_f32_16x16x32_bf16 v[30:33], v[140:143], v[222:225], v[30:33]
	v_mfma_f32_16x16x32_bf16 v[26:29], v[154:157], v[222:225], v[26:29]
	v_mfma_f32_16x16x32_bf16 v[14:17], v[140:143], v[230:233], v[14:17]
	v_mfma_f32_16x16x32_bf16 v[10:13], v[154:157], v[230:233], v[10:13]
	v_mfma_f32_16x16x32_bf16 v[62:65], v[150:153], v[210:213], v[62:65]
	v_mfma_f32_16x16x32_bf16 v[58:61], v[166:169], v[210:213], v[58:61]
	v_mfma_f32_16x16x32_bf16 v[46:49], v[150:153], v[218:221], v[46:49]
	v_mfma_f32_16x16x32_bf16 v[42:45], v[166:169], v[218:221], v[42:45]
	v_mfma_f32_16x16x32_bf16 v[30:33], v[150:153], v[226:229], v[30:33]
	v_mfma_f32_16x16x32_bf16 v[26:29], v[166:169], v[226:229], v[26:29]
	v_mfma_f32_16x16x32_bf16 v[14:17], v[150:153], v[234:237], v[14:17]
	v_mfma_f32_16x16x32_bf16 v[10:13], v[166:169], v[234:237], v[10:13]
	v_mfma_f32_16x16x32_bf16 v[54:57], v[170:173], v[206:209], v[54:57]
	v_mfma_f32_16x16x32_bf16 v[50:53], v[198:201], v[206:209], v[50:53]
	v_mfma_f32_16x16x32_bf16 v[38:41], v[170:173], v[214:217], v[38:41]
	v_mfma_f32_16x16x32_bf16 v[34:37], v[198:201], v[214:217], v[34:37]
	v_mfma_f32_16x16x32_bf16 v[22:25], v[170:173], v[222:225], v[22:25]
	v_mfma_f32_16x16x32_bf16 v[18:21], v[198:201], v[222:225], v[18:21]
	v_mfma_f32_16x16x32_bf16 v[6:9], v[170:173], v[230:233], v[6:9]
	v_mfma_f32_16x16x32_bf16 v[2:5], v[198:201], v[230:233], v[2:5]
	v_mfma_f32_16x16x32_bf16 v[54:57], v[174:177], v[210:213], v[54:57]
	v_mfma_f32_16x16x32_bf16 v[50:53], v[202:205], v[210:213], v[50:53]
	v_mfma_f32_16x16x32_bf16 v[38:41], v[174:177], v[218:221], v[38:41]
	v_mfma_f32_16x16x32_bf16 v[34:37], v[202:205], v[218:221], v[34:37]
	v_mfma_f32_16x16x32_bf16 v[22:25], v[174:177], v[226:229], v[22:25]
	v_mfma_f32_16x16x32_bf16 v[18:21], v[202:205], v[226:229], v[18:21]
	v_mfma_f32_16x16x32_bf16 v[6:9], v[174:177], v[234:237], v[6:9]
	v_mfma_f32_16x16x32_bf16 v[2:5], v[202:205], v[234:237], v[2:5]
	s_setprio 0
	s_barrier
	s_add_i32 s47, s47, 2
	s_add_u32 s22, s22, 0x100
	s_addc_u32 s23, s23, 0
	s_add_u32 s45, s45, 0x100
	s_addc_u32 s46, s46, 0
	s_cmp_gt_u32 s47, 13
	s_cbranch_scc0 .LBB0_1240
	s_and_b64 vcc, exec, s[12:13]
	s_cbranch_vccz .LBB0_1243
	s_barrier

.LBB0_1342:
	s_add_u32 s30, s28, 0x100
	s_addc_u32 s31, s29, 0
	s_add_i32 s57, 0, 0x10000
	s_cmp_eq_u32 s56, 60
	s_cselect_b32 s37, s11, s31
	s_cselect_b32 s36, s21, s30
	v_add_u32_e32 v148, s57, v151
	s_cselect_b32 s35, s19, s55
	s_cselect_b32 s34, s27, s54
	s_add_i32 s58, 0, 0x14000
	ds_read_b128 v[136:139], v148
	ds_read_b128 v[140:143], v148 offset:1024
	ds_read_b128 v[144:147], v148 offset:2048
	ds_read_b128 v[154:157], v148 offset:3072
	v_add_u32_e32 v148, s58, v151
	ds_read_b128 v[166:169], v148
	ds_read_b128 v[170:173], v148 offset:1024
	ds_read_b128 v[174:177], v148 offset:2048
	ds_read_b128 v[198:201], v148 offset:3072
	v_lshl_add_u64 v[148:149], s[28:29], 0, v[132:133]
	s_add_i32 m0, s44, 0xc000
	ds_read_b128 v[202:205], v153
	ds_read_b128 v[206:209], v153 offset:1024
	ds_read_b128 v[210:213], v153 offset:2048
	ds_read_b128 v[214:217], v153 offset:3072
	ds_read_b128 v[218:221], v153 offset:4096
	ds_read_b128 v[222:225], v153 offset:5120
	ds_read_b128 v[226:229], v153 offset:6144
	ds_read_b128 v[230:233], v153 offset:7168
	global_load_lds_dwordx4 v[148:149], off
	v_lshl_add_u64 v[148:149], s[28:29], 0, v[134:135]
	s_add_i32 m0, s44, 0xe000
	s_nop 0
	global_load_lds_dwordx4 v[148:149], off
	s_waitcnt vmcnt(8)
	s_waitcnt lgkmcnt(0)
	s_barrier
	s_setprio 1
	s_waitcnt lgkmcnt(0)
	v_mfma_f32_16x16x32_bf16 v[126:129], v[136:139], v[202:205], v[126:129]
	v_mfma_f32_16x16x32_bf16 v[122:125], v[144:147], v[202:205], v[122:125]
	v_mfma_f32_16x16x32_bf16 v[110:113], v[136:139], v[210:213], v[110:113]
	v_mfma_f32_16x16x32_bf16 v[106:109], v[144:147], v[210:213], v[106:109]
	v_mfma_f32_16x16x32_bf16 v[94:97], v[136:139], v[218:221], v[94:97]
	v_mfma_f32_16x16x32_bf16 v[90:93], v[144:147], v[218:221], v[90:93]
	v_mfma_f32_16x16x32_bf16 v[78:81], v[136:139], v[226:229], v[78:81]
	v_mfma_f32_16x16x32_bf16 v[74:77], v[144:147], v[226:229], v[74:77]
	v_mfma_f32_16x16x32_bf16 v[126:129], v[140:143], v[206:209], v[126:129]
	v_mfma_f32_16x16x32_bf16 v[122:125], v[154:157], v[206:209], v[122:125]
	v_mfma_f32_16x16x32_bf16 v[110:113], v[140:143], v[214:217], v[110:113]
	v_mfma_f32_16x16x32_bf16 v[106:109], v[154:157], v[214:217], v[106:109]
	v_mfma_f32_16x16x32_bf16 v[94:97], v[140:143], v[222:225], v[94:97]
	v_mfma_f32_16x16x32_bf16 v[90:93], v[154:157], v[222:225], v[90:93]
	v_mfma_f32_16x16x32_bf16 v[78:81], v[140:143], v[230:233], v[78:81]
	v_mfma_f32_16x16x32_bf16 v[74:77], v[154:157], v[230:233], v[74:77]
	v_mfma_f32_16x16x32_bf16 v[118:121], v[166:169], v[202:205], v[118:121]
	v_mfma_f32_16x16x32_bf16 v[114:117], v[174:177], v[202:205], v[114:117]
	v_mfma_f32_16x16x32_bf16 v[102:105], v[166:169], v[210:213], v[102:105]
	v_mfma_f32_16x16x32_bf16 v[98:101], v[174:177], v[210:213], v[98:101]
	v_mfma_f32_16x16x32_bf16 v[86:89], v[166:169], v[218:221], v[86:89]
	v_mfma_f32_16x16x32_bf16 v[82:85], v[174:177], v[218:221], v[82:85]
	v_mfma_f32_16x16x32_bf16 v[70:73], v[166:169], v[226:229], v[70:73]
	v_mfma_f32_16x16x32_bf16 v[66:69], v[174:177], v[226:229], v[66:69]
	v_mfma_f32_16x16x32_bf16 v[118:121], v[170:173], v[206:209], v[118:121]
	v_mfma_f32_16x16x32_bf16 v[114:117], v[198:201], v[206:209], v[114:117]
	v_mfma_f32_16x16x32_bf16 v[102:105], v[170:173], v[214:217], v[102:105]
	v_mfma_f32_16x16x32_bf16 v[98:101], v[198:201], v[214:217], v[98:101]
	v_mfma_f32_16x16x32_bf16 v[86:89], v[170:173], v[222:225], v[86:89]
	v_mfma_f32_16x16x32_bf16 v[82:85], v[198:201], v[222:225], v[82:85]
	v_mfma_f32_16x16x32_bf16 v[70:73], v[170:173], v[230:233], v[70:73]
	v_mfma_f32_16x16x32_bf16 v[66:69], v[198:201], v[230:233], v[66:69]
	s_setprio 0
	s_barrier
	s_add_i32 s28, s57, s43
	v_lshl_add_u64 v[148:149], s[34:35], 0, v[0:1]
	s_mov_b32 m0, s28
	ds_read_b128 v[202:205], v153 offset:16384
	ds_read_b128 v[206:209], v153 offset:17408
	ds_read_b128 v[210:213], v153 offset:18432
	ds_read_b128 v[214:217], v153 offset:19456
	ds_read_b128 v[218:221], v153 offset:20480
	ds_read_b128 v[222:225], v153 offset:21504
	ds_read_b128 v[226:229], v153 offset:22528
	ds_read_b128 v[230:233], v153 offset:23552
	global_load_lds_dwordx4 v[148:149], off
	s_add_i32 m0, s28, 0x2000
	s_add_u32 s28, s34, 0x100000
	v_lshl_add_u64 v[158:159], s[34:35], 0, v[130:131]
	s_addc_u32 s29, s35, 0
	s_add_i32 s57, s58, s43
	global_load_lds_dwordx4 v[158:159], off
	v_lshl_add_u64 v[162:163], s[28:29], 0, v[0:1]
	s_mov_b32 m0, s57
	v_lshl_add_u64 v[164:165], s[36:37], 0, v[130:131]
	global_load_lds_dwordx4 v[162:163], off
	v_lshl_add_u64 v[162:163], s[28:29], 0, v[130:131]
	s_add_i32 m0, s57, 0x2000
	s_nop 0
	global_load_lds_dwordx4 v[162:163], off
	v_lshl_add_u64 v[162:163], s[36:37], 0, v[0:1]
	s_mov_b32 m0, s44
	s_nop 0
	global_load_lds_dwordx4 v[162:163], off
	s_mov_b32 m0, s45
	s_nop 0
	global_load_lds_dwordx4 v[164:165], off
	s_waitcnt vmcnt(8)
	s_waitcnt lgkmcnt(0)
	s_barrier
	s_setprio 1
	s_waitcnt lgkmcnt(0)
	v_mfma_f32_16x16x32_bf16 v[62:65], v[136:139], v[202:205], v[62:65]
	v_mfma_f32_16x16x32_bf16 v[58:61], v[144:147], v[202:205], v[58:61]
	v_mfma_f32_16x16x32_bf16 v[46:49], v[136:139], v[210:213], v[46:49]
	v_mfma_f32_16x16x32_bf16 v[42:45], v[144:147], v[210:213], v[42:45]
	v_mfma_f32_16x16x32_bf16 v[30:33], v[136:139], v[218:221], v[30:33]
	v_mfma_f32_16x16x32_bf16 v[26:29], v[144:147], v[218:221], v[26:29]
	v_mfma_f32_16x16x32_bf16 v[14:17], v[136:139], v[226:229], v[14:17]
	v_mfma_f32_16x16x32_bf16 v[10:13], v[144:147], v[226:229], v[10:13]
	v_mfma_f32_16x16x32_bf16 v[62:65], v[140:143], v[206:209], v[62:65]
	v_mfma_f32_16x16x32_bf16 v[58:61], v[154:157], v[206:209], v[58:61]
	v_mfma_f32_16x16x32_bf16 v[46:49], v[140:143], v[214:217], v[46:49]
	v_mfma_f32_16x16x32_bf16 v[42:45], v[154:157], v[214:217], v[42:45]
	v_mfma_f32_16x16x32_bf16 v[30:33], v[140:143], v[222:225], v[30:33]
	v_mfma_f32_16x16x32_bf16 v[26:29], v[154:157], v[222:225], v[26:29]
	v_mfma_f32_16x16x32_bf16 v[14:17], v[140:143], v[230:233], v[14:17]
	v_mfma_f32_16x16x32_bf16 v[10:13], v[154:157], v[230:233], v[10:13]
	v_mfma_f32_16x16x32_bf16 v[54:57], v[166:169], v[202:205], v[54:57]
	v_mfma_f32_16x16x32_bf16 v[50:53], v[174:177], v[202:205], v[50:53]
	v_mfma_f32_16x16x32_bf16 v[38:41], v[166:169], v[210:213], v[38:41]
	v_mfma_f32_16x16x32_bf16 v[34:37], v[174:177], v[210:213], v[34:37]
	v_mfma_f32_16x16x32_bf16 v[22:25], v[166:169], v[218:221], v[22:25]
	v_mfma_f32_16x16x32_bf16 v[18:21], v[174:177], v[218:221], v[18:21]
	v_mfma_f32_16x16x32_bf16 v[6:9], v[166:169], v[226:229], v[6:9]
	v_mfma_f32_16x16x32_bf16 v[2:5], v[174:177], v[226:229], v[2:5]
	v_mfma_f32_16x16x32_bf16 v[54:57], v[170:173], v[206:209], v[54:57]
	v_mfma_f32_16x16x32_bf16 v[50:53], v[198:201], v[206:209], v[50:53]
	v_mfma_f32_16x16x32_bf16 v[38:41], v[170:173], v[214:217], v[38:41]
	v_mfma_f32_16x16x32_bf16 v[34:37], v[198:201], v[214:217], v[34:37]
	v_mfma_f32_16x16x32_bf16 v[22:25], v[170:173], v[222:225], v[22:25]
	v_mfma_f32_16x16x32_bf16 v[18:21], v[198:201], v[222:225], v[18:21]
	v_mfma_f32_16x16x32_bf16 v[6:9], v[170:173], v[230:233], v[6:9]
	v_mfma_f32_16x16x32_bf16 v[2:5], v[198:201], v[230:233], v[2:5]
	s_setprio 0
	s_barrier
	s_add_i32 s57, 0, 0x18000
	s_add_i32 s58, 0, 0x1c000
	v_add_u32_e32 v154, s57, v151
	v_add_u32_e32 v161, s58, v151
	ds_read_b128 v[136:139], v154
	ds_read_b128 v[140:143], v154 offset:1024
	ds_read_b128 v[144:147], v154 offset:2048
	ds_read_b128 v[154:157], v154 offset:3072
	ds_read_b128 v[166:169], v161
	ds_read_b128 v[170:173], v161 offset:1024
	ds_read_b128 v[174:177], v161 offset:2048
	ds_read_b128 v[198:201], v161 offset:3072
	s_add_u32 s28, s36, 0x100000
	s_addc_u32 s29, s37, 0
	s_mov_b32 m0, s46
	v_lshl_add_u64 v[178:179], s[28:29], 0, v[0:1]
	ds_read_b128 v[202:205], v153 offset:32768
	ds_read_b128 v[206:209], v153 offset:33792
	ds_read_b128 v[210:213], v153 offset:34816
	ds_read_b128 v[214:217], v153 offset:35840
	ds_read_b128 v[218:221], v153 offset:36864
	ds_read_b128 v[222:225], v153 offset:37888
	ds_read_b128 v[226:229], v153 offset:38912
	ds_read_b128 v[230:233], v153 offset:39936
	global_load_lds_dwordx4 v[178:179], off
	v_lshl_add_u64 v[178:179], s[28:29], 0, v[130:131]
	s_mov_b32 m0, s47
	s_nop 0
	global_load_lds_dwordx4 v[178:179], off
	s_waitcnt vmcnt(8)
	s_waitcnt lgkmcnt(0)
	s_barrier
	s_setprio 1
	s_waitcnt lgkmcnt(0)
	v_mfma_f32_16x16x32_bf16 v[126:129], v[136:139], v[202:205], v[126:129]
	v_mfma_f32_16x16x32_bf16 v[122:125], v[144:147], v[202:205], v[122:125]
	v_mfma_f32_16x16x32_bf16 v[110:113], v[136:139], v[210:213], v[110:113]
	v_mfma_f32_16x16x32_bf16 v[106:109], v[144:147], v[210:213], v[106:109]
	v_mfma_f32_16x16x32_bf16 v[94:97], v[136:139], v[218:221], v[94:97]
	v_mfma_f32_16x16x32_bf16 v[90:93], v[144:147], v[218:221], v[90:93]
	v_mfma_f32_16x16x32_bf16 v[78:81], v[136:139], v[226:229], v[78:81]
	v_mfma_f32_16x16x32_bf16 v[74:77], v[144:147], v[226:229], v[74:77]
	v_mfma_f32_16x16x32_bf16 v[126:129], v[140:143], v[206:209], v[126:129]
	v_mfma_f32_16x16x32_bf16 v[122:125], v[154:157], v[206:209], v[122:125]
	v_mfma_f32_16x16x32_bf16 v[110:113], v[140:143], v[214:217], v[110:113]
	v_mfma_f32_16x16x32_bf16 v[106:109], v[154:157], v[214:217], v[106:109]
	v_mfma_f32_16x16x32_bf16 v[94:97], v[140:143], v[222:225], v[94:97]
	v_mfma_f32_16x16x32_bf16 v[90:93], v[154:157], v[222:225], v[90:93]
	v_mfma_f32_16x16x32_bf16 v[78:81], v[140:143], v[230:233], v[78:81]
	v_mfma_f32_16x16x32_bf16 v[74:77], v[154:157], v[230:233], v[74:77]
	v_mfma_f32_16x16x32_bf16 v[118:121], v[166:169], v[202:205], v[118:121]
	v_mfma_f32_16x16x32_bf16 v[114:117], v[174:177], v[202:205], v[114:117]
	v_mfma_f32_16x16x32_bf16 v[102:105], v[166:169], v[210:213], v[102:105]
	v_mfma_f32_16x16x32_bf16 v[98:101], v[174:177], v[210:213], v[98:101]
	v_mfma_f32_16x16x32_bf16 v[86:89], v[166:169], v[218:221], v[86:89]
	v_mfma_f32_16x16x32_bf16 v[82:85], v[174:177], v[218:221], v[82:85]
	v_mfma_f32_16x16x32_bf16 v[70:73], v[166:169], v[226:229], v[70:73]
	v_mfma_f32_16x16x32_bf16 v[66:69], v[174:177], v[226:229], v[66:69]
	v_mfma_f32_16x16x32_bf16 v[118:121], v[170:173], v[206:209], v[118:121]
	v_mfma_f32_16x16x32_bf16 v[114:117], v[198:201], v[206:209], v[114:117]
	v_mfma_f32_16x16x32_bf16 v[102:105], v[170:173], v[214:217], v[102:105]
	v_mfma_f32_16x16x32_bf16 v[98:101], v[198:201], v[214:217], v[98:101]
	v_mfma_f32_16x16x32_bf16 v[86:89], v[170:173], v[222:225], v[86:89]
	v_mfma_f32_16x16x32_bf16 v[82:85], v[198:201], v[222:225], v[82:85]
	v_mfma_f32_16x16x32_bf16 v[70:73], v[170:173], v[230:233], v[70:73]
	v_mfma_f32_16x16x32_bf16 v[66:69], v[198:201], v[230:233], v[66:69]
	s_setprio 0
	s_barrier
	s_add_i32 s28, s57, s43
	v_lshl_add_u64 v[148:149], v[148:149], 0, s[88:89]
	s_mov_b32 m0, s28
	ds_read_b128 v[202:205], v153 offset:49152
	ds_read_b128 v[206:209], v153 offset:50176
	ds_read_b128 v[210:213], v153 offset:51200
	ds_read_b128 v[214:217], v153 offset:52224
	ds_read_b128 v[218:221], v153 offset:53248
	ds_read_b128 v[222:225], v153 offset:54272
	ds_read_b128 v[226:229], v153 offset:55296
	ds_read_b128 v[230:233], v153 offset:56320
	global_load_lds_dwordx4 v[148:149], off
	s_add_i32 m0, s28, 0x2000
	s_add_u32 s28, s34, 0x100080
	v_lshl_add_u64 v[148:149], v[158:159], 0, s[88:89]
	s_addc_u32 s29, s35, 0
	s_add_i32 s34, s58, s43
	global_load_lds_dwordx4 v[148:149], off
	v_lshl_add_u64 v[148:149], s[28:29], 0, v[0:1]
	s_mov_b32 m0, s34
	s_nop 0
	global_load_lds_dwordx4 v[148:149], off
	v_lshl_add_u64 v[148:149], s[28:29], 0, v[130:131]
	s_add_i32 m0, s34, 0x2000
	s_nop 0
	global_load_lds_dwordx4 v[148:149], off
	v_lshl_add_u64 v[148:149], v[162:163], 0, s[88:89]
	s_mov_b32 m0, s49
	s_nop 0
	global_load_lds_dwordx4 v[148:149], off
	v_lshl_add_u64 v[148:149], v[164:165], 0, s[88:89]
	s_mov_b32 m0, s50
	s_nop 0
	global_load_lds_dwordx4 v[148:149], off
	s_waitcnt vmcnt(8)
	s_waitcnt lgkmcnt(0)
	s_barrier
	s_setprio 1
	s_waitcnt lgkmcnt(0)
	v_mfma_f32_16x16x32_bf16 v[62:65], v[136:139], v[202:205], v[62:65]
	v_mfma_f32_16x16x32_bf16 v[58:61], v[144:147], v[202:205], v[58:61]
	v_mfma_f32_16x16x32_bf16 v[46:49], v[136:139], v[210:213], v[46:49]
	v_mfma_f32_16x16x32_bf16 v[42:45], v[144:147], v[210:213], v[42:45]
	v_mfma_f32_16x16x32_bf16 v[30:33], v[136:139], v[218:221], v[30:33]
	v_mfma_f32_16x16x32_bf16 v[26:29], v[144:147], v[218:221], v[26:29]
	v_mfma_f32_16x16x32_bf16 v[14:17], v[136:139], v[226:229], v[14:17]
	v_mfma_f32_16x16x32_bf16 v[10:13], v[144:147], v[226:229], v[10:13]
	v_mfma_f32_16x16x32_bf16 v[62:65], v[140:143], v[206:209], v[62:65]
	v_mfma_f32_16x16x32_bf16 v[58:61], v[154:157], v[206:209], v[58:61]
	v_mfma_f32_16x16x32_bf16 v[46:49], v[140:143], v[214:217], v[46:49]
	v_mfma_f32_16x16x32_bf16 v[42:45], v[154:157], v[214:217], v[42:45]
	v_mfma_f32_16x16x32_bf16 v[30:33], v[140:143], v[222:225], v[30:33]
	v_mfma_f32_16x16x32_bf16 v[26:29], v[154:157], v[222:225], v[26:29]
	v_mfma_f32_16x16x32_bf16 v[14:17], v[140:143], v[230:233], v[14:17]
	v_mfma_f32_16x16x32_bf16 v[10:13], v[154:157], v[230:233], v[10:13]
	v_mfma_f32_16x16x32_bf16 v[54:57], v[166:169], v[202:205], v[54:57]
	v_mfma_f32_16x16x32_bf16 v[50:53], v[174:177], v[202:205], v[50:53]
	v_mfma_f32_16x16x32_bf16 v[38:41], v[166:169], v[210:213], v[38:41]
	v_mfma_f32_16x16x32_bf16 v[34:37], v[174:177], v[210:213], v[34:37]
	v_mfma_f32_16x16x32_bf16 v[22:25], v[166:169], v[218:221], v[22:25]
	v_mfma_f32_16x16x32_bf16 v[18:21], v[174:177], v[218:221], v[18:21]
	v_mfma_f32_16x16x32_bf16 v[6:9], v[166:169], v[226:229], v[6:9]
	v_mfma_f32_16x16x32_bf16 v[2:5], v[174:177], v[226:229], v[2:5]
	v_mfma_f32_16x16x32_bf16 v[54:57], v[170:173], v[206:209], v[54:57]
	v_mfma_f32_16x16x32_bf16 v[50:53], v[198:201], v[206:209], v[50:53]
	v_mfma_f32_16x16x32_bf16 v[38:41], v[170:173], v[214:217], v[38:41]
	v_mfma_f32_16x16x32_bf16 v[34:37], v[198:201], v[214:217], v[34:37]
	v_mfma_f32_16x16x32_bf16 v[22:25], v[170:173], v[222:225], v[22:25]
	v_mfma_f32_16x16x32_bf16 v[18:21], v[198:201], v[222:225], v[18:21]
	v_mfma_f32_16x16x32_bf16 v[6:9], v[170:173], v[230:233], v[6:9]
	v_mfma_f32_16x16x32_bf16 v[2:5], v[198:201], v[230:233], v[2:5]
	s_setprio 0
	s_barrier
	s_add_i32 s56, s56, 2
	s_add_u32 s54, s54, 0x100
	s_addc_u32 s55, s55, 0
	s_cmp_gt_u32 s56, 61
	s_mov_b64 s[28:29], s[30:31]
	s_cbranch_scc0 .LBB0_1342
	s_and_b64 vcc, exec, s[16:17]
	s_cbranch_vccz .LBB0_1345
	s_barrier
